# v37: v32 + GEMM K-loop back-edge rotation (head scalar block + counter updates moved in front of the loop-back barrier) on G1/G3/G4/G5
# speedup vs baseline: 1.0012x; 1.0012x over previous
; #define PG8_STAGE(bufoff, gbase, voff) do { _Pragma("unroll") for (int _i = 0; _i < 2; ++_i) \
;         __builtin_amdgcn_global_load_lds((const unsigned*)((const char*)(gbase) + (voff)[_i]), (PG8_LAS unsigned*)(lds + (bufoff) + ldsw + _i * 8192), 16, 0, 0); } while (0)
; #define PG8_LDA(dst, b, h) do { _Pragma("unroll") for (int m = 0; m < 4; ++m) _Pragma("unroll") for (int k = 0; k < 2; ++k) dst[m][k] = *(const PG8_LAS bf16x8*)(lds + PG8_SA(b, h) + aoff + m * 2048 + k * 1024); } while (0)
; #define PG8_LDB(dst, b, h) do { _Pragma("unroll") for (int n = 0; n < 2; ++n) _Pragma("unroll") for (int k = 0; k < 2; ++k) dst[n][k] = *(const PG8_LAS bf16x8*)(lds + PG8_SB(b, h) + boff + n * 2048 + k * 1024); } while (0)
; #define PG8_WAIT_V(n) asm volatile("s_waitcnt vmcnt(" #n ")" ::: "memory")
; #define PG8_BAR __builtin_amdgcn_s_barrier()
; template <class Epi, class Sched, bool ALIGN_EPI = false, bool SP2 = false>
; __device__ __forceinline__ void gemm_phase(PG8_LAS unsigned char* lds, const Gemm g, const Sched& S, const Epi& E) {
;     ...
;         const bool has_next = S.next(ui + 1, nxt);
;         const char* nA = has_next ? (const char*)g.A + (size_t)nxt.pm * tstep + (size_t)nxt.kt0 * kstep : cA; const char* nB = has_next ? (const char*)g.Bt + (size_t)nxt.pn * tstep + (size_t)nxt.kt0 * kstep : cB;
;         const int nt = cur.nkt;
;         for (int t = 0; t < nt; t += 2) {
;             const bool last = (t == nt - 2);
;             const char* a1 = cA + (size_t)(t + 1) * kstep;
;             const char* a2 = last ? nA : cA + (size_t)(t + 2) * kstep; const char* b2 = last ? nB : cB + (size_t)(t + 2) * kstep;
;             const char* a3 = a2 + kstep; const char* b3 = b2 + kstep;
;             if (last && has_next) S.a_ready(nxt);
;             if constexpr (SP2) {
;             PG8_LDB(B0, 0, 0); PG8_LDB(B1, 0, 1); PG8_SCHED; PG8_LDA(At, 0, 0); PG8_STAGE(PG8_SA(1, 1), a1 + hstep, voffA);
;             PG8_WAIT_V(8); PG8_WAIT_L(0); PG8_BAR; PG8_MMA(0, 0, At, B0); PG8_MMA(0, 1, At, B1); PG8_BAR; PG8_SCHED;
;     ...
; #pragma unroll
;         for (int a = 0; a < 2; ++a)
; #pragma unroll
;             for (int b = 0; b < 2; ++b)
; #pragma unroll
;                 for (int m = 0; m < 4; ++m)
; #pragma unroll
;                     for (int n = 0; n < 2; ++n) acc[a][b][m][n] = (f32x4){0.f, 0.f, 0.f, 0.f};
;         cur = nxt; cA = nA; cB = nB; ++ui;
.LBB0_293:
	s_ashr_i32 s17, s16, 31
	s_lshl_b64 s[18:19], s[16:17], 19
	s_add_u32 s18, s0, s18
	s_addc_u32 s19, s28, s19
	s_and_b64 s[20:21], s[4:5], exec
	s_cselect_b32 s17, s19, s25
	s_cselect_b32 s42, s18, s24
	s_ashr_i32 s15, s14, 31
	s_lshl_b64 s[20:21], s[14:15], 19
	s_add_u32 s20, s29, s20
	s_addc_u32 s21, s30, s21
	s_and_b64 s[26:27], s[4:5], exec
	s_cselect_b32 s15, s21, s3
	s_cselect_b32 s43, s20, s2
	s_add_u32 s45, s2, 0x100
	s_addc_u32 s46, s3, 0
	s_add_u32 s2, s24, 0x40080
	v_mov_b32_e32 v0, 0
	s_addc_u32 s3, s25, 0
	s_mov_b32 s47, -2
	v_mov_b64_e32 v[0:1], 0
	v_mov_b64_e32 v[2:3], 0
	v_mov_b64_e32 v[8:9], 0
	v_mov_b64_e32 v[10:11], 0
	v_mov_b64_e32 v[16:17], 0
	v_mov_b64_e32 v[18:19], 0
	v_mov_b64_e32 v[24:25], 0
	v_mov_b64_e32 v[26:27], 0
	v_mov_b64_e32 v[32:33], 0
	v_mov_b64_e32 v[34:35], 0
	v_mov_b64_e32 v[40:41], 0
	v_mov_b64_e32 v[42:43], 0
	v_mov_b64_e32 v[48:49], 0
	v_mov_b64_e32 v[50:51], 0
	v_mov_b64_e32 v[56:57], 0
	v_mov_b64_e32 v[58:59], 0
	v_mov_b64_e32 v[4:5], 0
	v_mov_b64_e32 v[6:7], 0
	v_mov_b64_e32 v[12:13], 0
	v_mov_b64_e32 v[14:15], 0
	v_mov_b64_e32 v[20:21], 0
	v_mov_b64_e32 v[22:23], 0
	v_mov_b64_e32 v[28:29], 0
	v_mov_b64_e32 v[30:31], 0
	v_mov_b64_e32 v[36:37], 0
	v_mov_b64_e32 v[38:39], 0
	v_mov_b64_e32 v[44:45], 0
	v_mov_b64_e32 v[46:47], 0
	v_mov_b64_e32 v[52:53], 0
	v_mov_b64_e32 v[54:55], 0
	v_mov_b64_e32 v[60:61], 0
	v_mov_b64_e32 v[62:63], 0
	v_mov_b64_e32 v[64:65], 0
	v_mov_b64_e32 v[66:67], 0
	v_mov_b64_e32 v[72:73], 0
	v_mov_b64_e32 v[74:75], 0
	v_mov_b64_e32 v[80:81], 0
	v_mov_b64_e32 v[82:83], 0
	v_mov_b64_e32 v[88:89], 0
	v_mov_b64_e32 v[90:91], 0
	v_mov_b64_e32 v[96:97], 0
	v_mov_b64_e32 v[98:99], 0
	v_mov_b64_e32 v[104:105], 0
	v_mov_b64_e32 v[106:107], 0
	v_mov_b64_e32 v[112:113], 0
	v_mov_b64_e32 v[114:115], 0
	v_mov_b64_e32 v[120:121], 0
	v_mov_b64_e32 v[122:123], 0
	v_mov_b64_e32 v[68:69], 0
	v_mov_b64_e32 v[70:71], 0
	v_mov_b64_e32 v[76:77], 0
	v_mov_b64_e32 v[78:79], 0
	v_mov_b64_e32 v[84:85], 0
	v_mov_b64_e32 v[86:87], 0
	v_mov_b64_e32 v[92:93], 0
	v_mov_b64_e32 v[94:95], 0
	v_mov_b64_e32 v[100:101], 0
	v_mov_b64_e32 v[102:103], 0
	v_mov_b64_e32 v[108:109], 0
	v_mov_b64_e32 v[110:111], 0
	v_mov_b64_e32 v[116:117], 0
	v_mov_b64_e32 v[118:119], 0
	v_mov_b64_e32 v[124:125], 0
	v_mov_b64_e32 v[126:127], 0
	s_mov_b64 s[52:53], 0x80
	s_add_u32 s24, s2, 0xfffc0080
	s_addc_u32 s25, s3, -1
	s_add_i32 s48, 0, 0x10000
	s_cmp_eq_u32 s47, 12
	s_cselect_b32 s27, s17, s25
	s_cselect_b32 s26, s42, s24
	v_add_u32_e32 v142, s48, v156
	s_cselect_b32 s25, s15, s46
	s_cselect_b32 s24, s43, s45
	s_add_i32 s50, 0, 0x14000
.LBB0_294:
	ds_read_b128 v[138:141], v142
	ds_read_b128 v[160:163], v142 offset:1024
	ds_read_b128 v[164:167], v142 offset:2048
	ds_read_b128 v[168:171], v142 offset:3072
	v_add_u32_e32 v142, s50, v156
	ds_read_b128 v[172:175], v142
	ds_read_b128 v[176:179], v142 offset:1024
	ds_read_b128 v[180:183], v142 offset:2048
	ds_read_b128 v[184:187], v142 offset:3072
	v_lshl_add_u64 v[142:143], s[2:3], 0, v[136:137]
	s_add_i32 m0, s33, 0xc000
	ds_read_b128 v[188:191], v158
	ds_read_b128 v[192:195], v158 offset:1024
	ds_read_b128 v[196:199], v158 offset:2048
	ds_read_b128 v[200:203], v158 offset:3072
	ds_read_b128 v[204:207], v158 offset:4096
	ds_read_b128 v[208:211], v158 offset:5120
	ds_read_b128 v[234:237], v158 offset:6144
	ds_read_b128 v[244:247], v158 offset:7168
	global_load_lds_dwordx4 v[142:143], off
	v_lshl_add_u64 v[142:143], s[2:3], 0, v[134:135]
	s_add_i32 m0, s33, 0xe000
	s_nop 0
	global_load_lds_dwordx4 v[142:143], off
	s_waitcnt vmcnt(8)
	s_waitcnt lgkmcnt(0)
	s_barrier
	s_setprio 1
	s_waitcnt lgkmcnt(0)
	v_mfma_f32_16x16x32_bf16 v[124:127], v[138:141], v[188:191], v[124:127]
	v_mfma_f32_16x16x32_bf16 v[116:119], v[164:167], v[188:191], v[116:119]
	v_mfma_f32_16x16x32_bf16 v[108:111], v[138:141], v[196:199], v[108:111]
	v_mfma_f32_16x16x32_bf16 v[100:103], v[164:167], v[196:199], v[100:103]
	v_mfma_f32_16x16x32_bf16 v[92:95], v[138:141], v[204:207], v[92:95]
	v_mfma_f32_16x16x32_bf16 v[84:87], v[164:167], v[204:207], v[84:87]
	v_mfma_f32_16x16x32_bf16 v[76:79], v[138:141], v[234:237], v[76:79]
	v_mfma_f32_16x16x32_bf16 v[68:71], v[164:167], v[234:237], v[68:71]
	v_mfma_f32_16x16x32_bf16 v[124:127], v[160:163], v[192:195], v[124:127]
	v_mfma_f32_16x16x32_bf16 v[116:119], v[168:171], v[192:195], v[116:119]
	v_mfma_f32_16x16x32_bf16 v[108:111], v[160:163], v[200:203], v[108:111]
	v_mfma_f32_16x16x32_bf16 v[100:103], v[168:171], v[200:203], v[100:103]
	v_mfma_f32_16x16x32_bf16 v[92:95], v[160:163], v[208:211], v[92:95]
	v_mfma_f32_16x16x32_bf16 v[84:87], v[168:171], v[208:211], v[84:87]
	v_mfma_f32_16x16x32_bf16 v[76:79], v[160:163], v[244:247], v[76:79]
	v_mfma_f32_16x16x32_bf16 v[68:71], v[168:171], v[244:247], v[68:71]
	s_setprio 0
	s_setprio 1
	v_mfma_f32_16x16x32_bf16 v[120:123], v[172:175], v[188:191], v[120:123]
	v_mfma_f32_16x16x32_bf16 v[112:115], v[180:183], v[188:191], v[112:115]
	v_mfma_f32_16x16x32_bf16 v[104:107], v[172:175], v[196:199], v[104:107]
	v_mfma_f32_16x16x32_bf16 v[96:99], v[180:183], v[196:199], v[96:99]
	v_mfma_f32_16x16x32_bf16 v[88:91], v[172:175], v[204:207], v[88:91]
	v_mfma_f32_16x16x32_bf16 v[80:83], v[180:183], v[204:207], v[80:83]
	v_mfma_f32_16x16x32_bf16 v[72:75], v[172:175], v[234:237], v[72:75]
	v_mfma_f32_16x16x32_bf16 v[64:67], v[180:183], v[234:237], v[64:67]
	v_mfma_f32_16x16x32_bf16 v[120:123], v[176:179], v[192:195], v[120:123]
	v_mfma_f32_16x16x32_bf16 v[112:115], v[184:187], v[192:195], v[112:115]
	v_mfma_f32_16x16x32_bf16 v[104:107], v[176:179], v[200:203], v[104:107]
	v_mfma_f32_16x16x32_bf16 v[96:99], v[184:187], v[200:203], v[96:99]
	v_mfma_f32_16x16x32_bf16 v[88:91], v[176:179], v[208:211], v[88:91]
	v_mfma_f32_16x16x32_bf16 v[80:83], v[184:187], v[208:211], v[80:83]
	v_mfma_f32_16x16x32_bf16 v[72:75], v[176:179], v[244:247], v[72:75]
	v_mfma_f32_16x16x32_bf16 v[64:67], v[184:187], v[244:247], v[64:67]
	s_setprio 0
	s_barrier
; #define PG8_STAGE(bufoff, gbase, voff) do { _Pragma("unroll") for (int _i = 0; _i < 2; ++_i) \
;         __builtin_amdgcn_global_load_lds((const unsigned*)((const char*)(gbase) + (voff)[_i]), (PG8_LAS unsigned*)(lds + (bufoff) + ldsw + _i * 8192), 16, 0, 0); } while (0)
; #define PG8_LDA(dst, b, h) do { _Pragma("unroll") for (int m = 0; m < 4; ++m) _Pragma("unroll") for (int k = 0; k < 2; ++k) dst[m][k] = *(const PG8_LAS bf16x8*)(lds + PG8_SA(b, h) + aoff + m * 2048 + k * 1024); } while (0)
; #define PG8_LDB(dst, b, h) do { _Pragma("unroll") for (int n = 0; n < 2; ++n) _Pragma("unroll") for (int k = 0; k < 2; ++k) dst[n][k] = *(const PG8_LAS bf16x8*)(lds + PG8_SB(b, h) + boff + n * 2048 + k * 1024); } while (0)
; #define PG8_MMA(ai, bj, At, Bt) do { __builtin_amdgcn_s_setprio(1); _Pragma("unroll") for (int m = 0; m < 4; ++m) _Pragma("unroll") for (int n = 0; n < 2; ++n) _Pragma("unroll") for (int k = 0; k < 2; ++k) \
;         acc[ai][bj][m][n] = __builtin_amdgcn_mfma_f32_16x16x32_bf16(Bt[n][k], At[m][k], acc[ai][bj][m][n], 0, 0, 0); __builtin_amdgcn_s_setprio(0); } while (0)
; #define PG8_WAIT_V(n) asm volatile("s_waitcnt vmcnt(" #n ")" ::: "memory")
; #define PG8_WAIT_L(n) asm volatile("s_waitcnt lgkmcnt(" #n ")" ::: "memory")
; #define PG8_BAR __builtin_amdgcn_s_barrier()
; #define PG8_SCHED __builtin_amdgcn_sched_barrier(0)
; template <class Epi, class Sched, bool ALIGN_EPI = false, bool SP2 = false>
; __device__ __forceinline__ void gemm_phase(PG8_LAS unsigned char* lds, const Gemm g, const Sched& S, const Epi& E) {
;     ...
;             PG8_LDB(B0, 0, 0); PG8_LDB(B1, 0, 1); PG8_SCHED; PG8_LDA(At, 0, 0); PG8_STAGE(PG8_SA(1, 1), a1 + hstep, voffA);
;             PG8_WAIT_V(8); PG8_WAIT_L(0); PG8_BAR; PG8_MMA(0, 0, At, B0); PG8_MMA(0, 1, At, B1); PG8_BAR; PG8_SCHED;
;             PG8_LDA(At, 0, 1); PG8_STAGE(PG8_SB(0, 0), b2, voffB); PG8_STAGE(PG8_SB(0, 1), b2 + hstep, voffB); PG8_STAGE(PG8_SA(0, 0), a2, voffA);
;             PG8_WAIT_V(8); PG8_WAIT_L(0); PG8_BAR; PG8_MMA(1, 0, At, B0); PG8_MMA(1, 1, At, B1); PG8_BAR; PG8_SCHED;
;             PG8_LDB(B0, 1, 0); PG8_LDB(B1, 1, 1); PG8_SCHED; PG8_LDA(At, 1, 0); PG8_STAGE(PG8_SA(0, 1), a2 + hstep, voffA);
;             PG8_WAIT_V(8); PG8_WAIT_L(0); PG8_BAR; PG8_MMA(0, 0, At, B0); PG8_MMA(0, 1, At, B1); PG8_BAR; PG8_SCHED;
	s_add_i32 s48, s48, s31
	v_lshl_add_u64 v[142:143], s[24:25], 0, v[144:145]
	s_mov_b32 m0, s48
	ds_read_b128 v[188:191], v158 offset:16384
	ds_read_b128 v[192:195], v158 offset:17408
	ds_read_b128 v[196:199], v158 offset:18432
	ds_read_b128 v[200:203], v158 offset:19456
	ds_read_b128 v[204:207], v158 offset:20480
	ds_read_b128 v[208:211], v158 offset:21504
	ds_read_b128 v[234:237], v158 offset:22528
	ds_read_b128 v[244:247], v158 offset:23552
	global_load_lds_dwordx4 v[142:143], off
	s_add_i32 m0, s48, 0x2000
	s_add_u32 s48, s24, 0x40000
	v_lshl_add_u64 v[238:239], s[24:25], 0, v[128:129]
	s_addc_u32 s49, s25, 0
	s_add_i32 s50, s50, s31
	global_load_lds_dwordx4 v[238:239], off
	v_lshl_add_u64 v[248:249], s[48:49], 0, v[144:145]
	s_mov_b32 m0, s50
	v_lshl_add_u64 v[250:251], s[26:27], 0, v[130:131]
	global_load_lds_dwordx4 v[248:249], off
	v_lshl_add_u64 v[248:249], s[48:49], 0, v[128:129]
	s_add_i32 m0, s50, 0x2000
	s_nop 0
	global_load_lds_dwordx4 v[248:249], off
	v_lshl_add_u64 v[248:249], s[26:27], 0, v[132:133]
	s_mov_b32 m0, s33
	s_nop 0
	global_load_lds_dwordx4 v[248:249], off
	s_mov_b32 m0, s34
	s_nop 0
	global_load_lds_dwordx4 v[250:251], off
	s_waitcnt vmcnt(8)
	s_waitcnt lgkmcnt(0)
	s_barrier
	s_setprio 1
	s_waitcnt lgkmcnt(0)
	v_mfma_f32_16x16x32_bf16 v[60:63], v[138:141], v[188:191], v[60:63]
	v_mfma_f32_16x16x32_bf16 v[52:55], v[164:167], v[188:191], v[52:55]
	v_mfma_f32_16x16x32_bf16 v[44:47], v[138:141], v[196:199], v[44:47]
	v_mfma_f32_16x16x32_bf16 v[36:39], v[164:167], v[196:199], v[36:39]
	v_mfma_f32_16x16x32_bf16 v[28:31], v[138:141], v[204:207], v[28:31]
	v_mfma_f32_16x16x32_bf16 v[20:23], v[164:167], v[204:207], v[20:23]
	v_mfma_f32_16x16x32_bf16 v[12:15], v[138:141], v[234:237], v[12:15]
	v_mfma_f32_16x16x32_bf16 v[4:7], v[164:167], v[234:237], v[4:7]
	v_mfma_f32_16x16x32_bf16 v[60:63], v[160:163], v[192:195], v[60:63]
	v_mfma_f32_16x16x32_bf16 v[52:55], v[168:171], v[192:195], v[52:55]
	v_mfma_f32_16x16x32_bf16 v[44:47], v[160:163], v[200:203], v[44:47]
	v_mfma_f32_16x16x32_bf16 v[36:39], v[168:171], v[200:203], v[36:39]
	v_mfma_f32_16x16x32_bf16 v[28:31], v[160:163], v[208:211], v[28:31]
	v_mfma_f32_16x16x32_bf16 v[20:23], v[168:171], v[208:211], v[20:23]
	v_mfma_f32_16x16x32_bf16 v[12:15], v[160:163], v[244:247], v[12:15]
	v_mfma_f32_16x16x32_bf16 v[4:7], v[168:171], v[244:247], v[4:7]
	s_setprio 0
	s_setprio 1
	v_mfma_f32_16x16x32_bf16 v[56:59], v[172:175], v[188:191], v[56:59]
	v_mfma_f32_16x16x32_bf16 v[48:51], v[180:183], v[188:191], v[48:51]
	v_mfma_f32_16x16x32_bf16 v[40:43], v[172:175], v[196:199], v[40:43]
	v_mfma_f32_16x16x32_bf16 v[32:35], v[180:183], v[196:199], v[32:35]
	v_mfma_f32_16x16x32_bf16 v[24:27], v[172:175], v[204:207], v[24:27]
	v_mfma_f32_16x16x32_bf16 v[16:19], v[180:183], v[204:207], v[16:19]
	v_mfma_f32_16x16x32_bf16 v[8:11], v[172:175], v[234:237], v[8:11]
	v_mfma_f32_16x16x32_bf16 v[0:3], v[180:183], v[234:237], v[0:3]
	v_mfma_f32_16x16x32_bf16 v[56:59], v[176:179], v[192:195], v[56:59]
	v_mfma_f32_16x16x32_bf16 v[48:51], v[184:187], v[192:195], v[48:51]
	v_mfma_f32_16x16x32_bf16 v[40:43], v[176:179], v[200:203], v[40:43]
	v_mfma_f32_16x16x32_bf16 v[32:35], v[184:187], v[200:203], v[32:35]
	v_mfma_f32_16x16x32_bf16 v[24:27], v[176:179], v[208:211], v[24:27]
	v_mfma_f32_16x16x32_bf16 v[16:19], v[184:187], v[208:211], v[16:19]
	v_mfma_f32_16x16x32_bf16 v[8:11], v[176:179], v[244:247], v[8:11]
	v_mfma_f32_16x16x32_bf16 v[0:3], v[184:187], v[244:247], v[0:3]
	s_setprio 0
	s_barrier
	s_add_i32 s48, 0, 0x18000
	v_add_u32_e32 v154, s48, v156
	s_add_i32 s49, 0, 0x1c000
	ds_read_b128 v[138:141], v154
	ds_read_b128 v[160:163], v154 offset:1024
	ds_read_b128 v[164:167], v154 offset:2048
	ds_read_b128 v[168:171], v154 offset:3072
	v_add_u32_e32 v154, s49, v156
	ds_read_b128 v[172:175], v154
	ds_read_b128 v[176:179], v154 offset:1024
	ds_read_b128 v[180:183], v154 offset:2048
	ds_read_b128 v[184:187], v154 offset:3072
	s_add_u32 s26, s26, 0x40000
	s_addc_u32 s27, s27, 0
	s_mov_b32 m0, s35
	v_lshl_add_u64 v[252:253], s[26:27], 0, v[132:133]
	ds_read_b128 v[188:191], v158 offset:32768
	ds_read_b128 v[192:195], v158 offset:33792
	ds_read_b128 v[196:199], v158 offset:34816
	ds_read_b128 v[200:203], v158 offset:35840
	ds_read_b128 v[204:207], v158 offset:36864
	ds_read_b128 v[208:211], v158 offset:37888
	ds_read_b128 v[234:237], v158 offset:38912
	ds_read_b128 v[244:247], v158 offset:39936
	global_load_lds_dwordx4 v[252:253], off
	v_lshl_add_u64 v[252:253], s[26:27], 0, v[130:131]
	s_mov_b32 m0, s36
	s_nop 0
	global_load_lds_dwordx4 v[252:253], off
	s_waitcnt vmcnt(8)
	s_waitcnt lgkmcnt(0)
	s_barrier
; #define PG8_STAGE(bufoff, gbase, voff) do { _Pragma("unroll") for (int _i = 0; _i < 2; ++_i) \
;         __builtin_amdgcn_global_load_lds((const unsigned*)((const char*)(gbase) + (voff)[_i]), (PG8_LAS unsigned*)(lds + (bufoff) + ldsw + _i * 8192), 16, 0, 0); } while (0)
; #define PG8_LDA(dst, b, h) do { _Pragma("unroll") for (int m = 0; m < 4; ++m) _Pragma("unroll") for (int k = 0; k < 2; ++k) dst[m][k] = *(const PG8_LAS bf16x8*)(lds + PG8_SA(b, h) + aoff + m * 2048 + k * 1024); } while (0)
; #define PG8_MMA(ai, bj, At, Bt) do { __builtin_amdgcn_s_setprio(1); _Pragma("unroll") for (int m = 0; m < 4; ++m) _Pragma("unroll") for (int n = 0; n < 2; ++n) _Pragma("unroll") for (int k = 0; k < 2; ++k) \
;         acc[ai][bj][m][n] = __builtin_amdgcn_mfma_f32_16x16x32_bf16(Bt[n][k], At[m][k], acc[ai][bj][m][n], 0, 0, 0); __builtin_amdgcn_s_setprio(0); } while (0)
; #define PG8_WAIT_V(n) asm volatile("s_waitcnt vmcnt(" #n ")" ::: "memory")
; #define PG8_WAIT_L(n) asm volatile("s_waitcnt lgkmcnt(" #n ")" ::: "memory")
; #define PG8_BAR __builtin_amdgcn_s_barrier()
; #define PG8_SCHED __builtin_amdgcn_sched_barrier(0)
; template <class Epi, class Sched, bool ALIGN_EPI = false, bool SP2 = false>
; __device__ __forceinline__ void gemm_phase(PG8_LAS unsigned char* lds, const Gemm g, const Sched& S, const Epi& E) {
;     ...
;         for (int t = 0; t < nt; t += 2) {
;             const bool last = (t == nt - 2);
;             const char* a1 = cA + (size_t)(t + 1) * kstep;
;             const char* a2 = last ? nA : cA + (size_t)(t + 2) * kstep; const char* b2 = last ? nB : cB + (size_t)(t + 2) * kstep;
;             const char* a3 = a2 + kstep; const char* b3 = b2 + kstep;
;     ...
;             PG8_WAIT_V(8); PG8_WAIT_L(0); PG8_BAR; PG8_MMA(0, 0, At, B0); PG8_MMA(0, 1, At, B1); PG8_BAR; PG8_SCHED;
;             PG8_LDA(At, 1, 1); PG8_STAGE(PG8_SB(1, 0), b3, voffB); PG8_STAGE(PG8_SB(1, 1), b3 + hstep, voffB); PG8_STAGE(PG8_SA(1, 0), a3, voffA);
;             PG8_WAIT_V(8); PG8_WAIT_L(0); PG8_BAR; PG8_MMA(1, 0, At, B0); PG8_MMA(1, 1, At, B1); PG8_BAR; PG8_SCHED;
	s_setprio 1
	s_waitcnt lgkmcnt(0)
	v_mfma_f32_16x16x32_bf16 v[124:127], v[138:141], v[188:191], v[124:127]
	v_mfma_f32_16x16x32_bf16 v[116:119], v[164:167], v[188:191], v[116:119]
	v_mfma_f32_16x16x32_bf16 v[108:111], v[138:141], v[196:199], v[108:111]
	v_mfma_f32_16x16x32_bf16 v[100:103], v[164:167], v[196:199], v[100:103]
	v_mfma_f32_16x16x32_bf16 v[92:95], v[138:141], v[204:207], v[92:95]
	v_mfma_f32_16x16x32_bf16 v[84:87], v[164:167], v[204:207], v[84:87]
	v_mfma_f32_16x16x32_bf16 v[76:79], v[138:141], v[234:237], v[76:79]
	v_mfma_f32_16x16x32_bf16 v[68:71], v[164:167], v[234:237], v[68:71]
	v_mfma_f32_16x16x32_bf16 v[124:127], v[160:163], v[192:195], v[124:127]
	v_mfma_f32_16x16x32_bf16 v[116:119], v[168:171], v[192:195], v[116:119]
	v_mfma_f32_16x16x32_bf16 v[108:111], v[160:163], v[200:203], v[108:111]
	v_mfma_f32_16x16x32_bf16 v[100:103], v[168:171], v[200:203], v[100:103]
	v_mfma_f32_16x16x32_bf16 v[92:95], v[160:163], v[208:211], v[92:95]
	v_mfma_f32_16x16x32_bf16 v[84:87], v[168:171], v[208:211], v[84:87]
	v_mfma_f32_16x16x32_bf16 v[76:79], v[160:163], v[244:247], v[76:79]
	v_mfma_f32_16x16x32_bf16 v[68:71], v[168:171], v[244:247], v[68:71]
	s_setprio 0
	s_setprio 1
	v_mfma_f32_16x16x32_bf16 v[120:123], v[172:175], v[188:191], v[120:123]
	v_mfma_f32_16x16x32_bf16 v[112:115], v[180:183], v[188:191], v[112:115]
	v_mfma_f32_16x16x32_bf16 v[104:107], v[172:175], v[196:199], v[104:107]
	v_mfma_f32_16x16x32_bf16 v[96:99], v[180:183], v[196:199], v[96:99]
	v_mfma_f32_16x16x32_bf16 v[88:91], v[172:175], v[204:207], v[88:91]
	v_mfma_f32_16x16x32_bf16 v[80:83], v[180:183], v[204:207], v[80:83]
	v_mfma_f32_16x16x32_bf16 v[72:75], v[172:175], v[234:237], v[72:75]
	v_mfma_f32_16x16x32_bf16 v[64:67], v[180:183], v[234:237], v[64:67]
	v_mfma_f32_16x16x32_bf16 v[120:123], v[176:179], v[192:195], v[120:123]
	v_mfma_f32_16x16x32_bf16 v[112:115], v[184:187], v[192:195], v[112:115]
	v_mfma_f32_16x16x32_bf16 v[104:107], v[176:179], v[200:203], v[104:107]
	v_mfma_f32_16x16x32_bf16 v[96:99], v[184:187], v[200:203], v[96:99]
	v_mfma_f32_16x16x32_bf16 v[88:91], v[176:179], v[208:211], v[88:91]
	v_mfma_f32_16x16x32_bf16 v[80:83], v[184:187], v[208:211], v[80:83]
	v_mfma_f32_16x16x32_bf16 v[72:75], v[176:179], v[244:247], v[72:75]
	v_mfma_f32_16x16x32_bf16 v[64:67], v[184:187], v[244:247], v[64:67]
	s_setprio 0
	s_barrier
	s_add_i32 s26, s48, s31
	v_lshl_add_u64 v[142:143], v[142:143], 0, s[52:53]
	s_mov_b32 m0, s26
	ds_read_b128 v[188:191], v158 offset:49152
	ds_read_b128 v[192:195], v158 offset:50176
	ds_read_b128 v[196:199], v158 offset:51200
	ds_read_b128 v[200:203], v158 offset:52224
	ds_read_b128 v[204:207], v158 offset:53248
	ds_read_b128 v[208:211], v158 offset:54272
	ds_read_b128 v[234:237], v158 offset:55296
	ds_read_b128 v[244:247], v158 offset:56320
	global_load_lds_dwordx4 v[142:143], off
	s_add_i32 m0, s26, 0x2000
	s_add_u32 s24, s24, 0x40080
	v_lshl_add_u64 v[142:143], v[238:239], 0, s[52:53]
	s_addc_u32 s25, s25, 0
	s_add_i32 s26, s49, s31
	global_load_lds_dwordx4 v[142:143], off
	v_lshl_add_u64 v[142:143], s[24:25], 0, v[144:145]
	s_mov_b32 m0, s26
	s_nop 0
	global_load_lds_dwordx4 v[142:143], off
	v_lshl_add_u64 v[142:143], s[24:25], 0, v[128:129]
	s_add_i32 m0, s26, 0x2000
	s_nop 0
	global_load_lds_dwordx4 v[142:143], off
	v_lshl_add_u64 v[142:143], v[248:249], 0, s[52:53]
	s_mov_b32 m0, s37
	s_nop 0
	global_load_lds_dwordx4 v[142:143], off
	v_lshl_add_u64 v[142:143], v[250:251], 0, s[52:53]
	s_mov_b32 m0, s38
	s_nop 0
	global_load_lds_dwordx4 v[142:143], off
	s_waitcnt vmcnt(8)
	s_waitcnt lgkmcnt(0)
	s_barrier
	s_setprio 1
	s_waitcnt lgkmcnt(0)
	v_mfma_f32_16x16x32_bf16 v[60:63], v[138:141], v[188:191], v[60:63]
	v_mfma_f32_16x16x32_bf16 v[52:55], v[164:167], v[188:191], v[52:55]
	v_mfma_f32_16x16x32_bf16 v[44:47], v[138:141], v[196:199], v[44:47]
	v_mfma_f32_16x16x32_bf16 v[36:39], v[164:167], v[196:199], v[36:39]
	v_mfma_f32_16x16x32_bf16 v[28:31], v[138:141], v[204:207], v[28:31]
	v_mfma_f32_16x16x32_bf16 v[20:23], v[164:167], v[204:207], v[20:23]
	v_mfma_f32_16x16x32_bf16 v[12:15], v[138:141], v[234:237], v[12:15]
	v_mfma_f32_16x16x32_bf16 v[4:7], v[164:167], v[234:237], v[4:7]
	v_mfma_f32_16x16x32_bf16 v[60:63], v[160:163], v[192:195], v[60:63]
	v_mfma_f32_16x16x32_bf16 v[52:55], v[168:171], v[192:195], v[52:55]
	v_mfma_f32_16x16x32_bf16 v[44:47], v[160:163], v[200:203], v[44:47]
	v_mfma_f32_16x16x32_bf16 v[36:39], v[168:171], v[200:203], v[36:39]
	v_mfma_f32_16x16x32_bf16 v[28:31], v[160:163], v[208:211], v[28:31]
	v_mfma_f32_16x16x32_bf16 v[20:23], v[168:171], v[208:211], v[20:23]
	v_mfma_f32_16x16x32_bf16 v[12:15], v[160:163], v[244:247], v[12:15]
	v_mfma_f32_16x16x32_bf16 v[4:7], v[168:171], v[244:247], v[4:7]
	s_setprio 0
	s_setprio 1
	v_mfma_f32_16x16x32_bf16 v[56:59], v[172:175], v[188:191], v[56:59]
	v_mfma_f32_16x16x32_bf16 v[48:51], v[180:183], v[188:191], v[48:51]
	v_mfma_f32_16x16x32_bf16 v[40:43], v[172:175], v[196:199], v[40:43]
	v_mfma_f32_16x16x32_bf16 v[32:35], v[180:183], v[196:199], v[32:35]
	v_mfma_f32_16x16x32_bf16 v[24:27], v[172:175], v[204:207], v[24:27]
	v_mfma_f32_16x16x32_bf16 v[16:19], v[180:183], v[204:207], v[16:19]
	v_mfma_f32_16x16x32_bf16 v[8:11], v[172:175], v[234:237], v[8:11]
	v_mfma_f32_16x16x32_bf16 v[0:3], v[180:183], v[234:237], v[0:3]
	v_mfma_f32_16x16x32_bf16 v[56:59], v[176:179], v[192:195], v[56:59]
	v_mfma_f32_16x16x32_bf16 v[48:51], v[184:187], v[192:195], v[48:51]
	v_mfma_f32_16x16x32_bf16 v[40:43], v[176:179], v[200:203], v[40:43]
	v_mfma_f32_16x16x32_bf16 v[32:35], v[184:187], v[200:203], v[32:35]
	v_mfma_f32_16x16x32_bf16 v[24:27], v[176:179], v[208:211], v[24:27]
	v_mfma_f32_16x16x32_bf16 v[16:19], v[184:187], v[208:211], v[16:19]
	v_mfma_f32_16x16x32_bf16 v[8:11], v[176:179], v[244:247], v[8:11]
	v_mfma_f32_16x16x32_bf16 v[0:3], v[184:187], v[244:247], v[0:3]
	s_setprio 0
	s_add_i32 s47, s47, 2
	s_add_u32 s45, s45, 0x100
	s_addc_u32 s46, s46, 0
	s_add_u32 s2, s2, 0x100
	s_addc_u32 s3, s3, 0
	s_add_u32 s24, s2, 0xfffc0080
	s_addc_u32 s25, s3, -1
	s_add_i32 s48, 0, 0x10000
	s_cmp_eq_u32 s47, 12
	s_cselect_b32 s27, s17, s25
	s_cselect_b32 s26, s42, s24
	v_add_u32_e32 v142, s48, v156
	s_cselect_b32 s25, s15, s46
	s_cselect_b32 s24, s43, s45
	s_add_i32 s50, 0, 0x14000
	s_barrier
	s_cmp_gt_u32 s47, 13
	s_cbranch_scc0 .LBB0_294
	s_and_b64 vcc, exec, s[12:13]
	s_cbranch_vccz .LBB0_297
	s_barrier

; #define PG8_STAGE(bufoff, gbase, voff) do { _Pragma("unroll") for (int _i = 0; _i < 2; ++_i) \
;         __builtin_amdgcn_global_load_lds((const unsigned*)((const char*)(gbase) + (voff)[_i]), (PG8_LAS unsigned*)(lds + (bufoff) + ldsw + _i * 8192), 16, 0, 0); } while (0)
; #define PG8_LDA(dst, b, h) do { _Pragma("unroll") for (int m = 0; m < 4; ++m) _Pragma("unroll") for (int k = 0; k < 2; ++k) dst[m][k] = *(const PG8_LAS bf16x8*)(lds + PG8_SA(b, h) + aoff + m * 2048 + k * 1024); } while (0)
; #define PG8_LDB(dst, b, h) do { _Pragma("unroll") for (int n = 0; n < 2; ++n) _Pragma("unroll") for (int k = 0; k < 2; ++k) dst[n][k] = *(const PG8_LAS bf16x8*)(lds + PG8_SB(b, h) + boff + n * 2048 + k * 1024); } while (0)
; #define PG8_WAIT_V(n) asm volatile("s_waitcnt vmcnt(" #n ")" ::: "memory")
; #define PG8_BAR __builtin_amdgcn_s_barrier()
; template <class Epi, class Sched, bool ALIGN_EPI = false, bool SP2 = false>
; __device__ __forceinline__ void gemm_phase(PG8_LAS unsigned char* lds, const Gemm g, const Sched& S, const Epi& E) {
;     ...
;         const bool has_next = S.next(ui + 1, nxt);
;         const char* nA = has_next ? (const char*)g.A + (size_t)nxt.pm * tstep + (size_t)nxt.kt0 * kstep : cA; const char* nB = has_next ? (const char*)g.Bt + (size_t)nxt.pn * tstep + (size_t)nxt.kt0 * kstep : cB;
;         const int nt = cur.nkt;
;         for (int t = 0; t < nt; t += 2) {
;             const bool last = (t == nt - 2);
;             const char* a1 = cA + (size_t)(t + 1) * kstep;
;             const char* a2 = last ? nA : cA + (size_t)(t + 2) * kstep; const char* b2 = last ? nB : cB + (size_t)(t + 2) * kstep;
;             const char* a3 = a2 + kstep; const char* b3 = b2 + kstep;
;             if (last && has_next) S.a_ready(nxt);
;             if constexpr (SP2) {
;             PG8_LDB(B0, 0, 0); PG8_LDB(B1, 0, 1); PG8_SCHED; PG8_LDA(At, 0, 0); PG8_STAGE(PG8_SA(1, 1), a1 + hstep, voffA);
;             PG8_WAIT_V(8); PG8_WAIT_L(0); PG8_BAR; PG8_MMA(0, 0, At, B0); PG8_MMA(0, 1, At, B1); PG8_BAR; PG8_SCHED;
;     ...
; #pragma unroll
;         for (int a = 0; a < 2; ++a)
; #pragma unroll
;             for (int b = 0; b < 2; ++b)
; #pragma unroll
;                 for (int m = 0; m < 4; ++m)
; #pragma unroll
;                     for (int n = 0; n < 2; ++n) acc[a][b][m][n] = (f32x4){0.f, 0.f, 0.f, 0.f};
;         cur = nxt; cA = nA; cB = nB; ++ui;
.LBB0_538:
	s_ashr_i32 s13, s12, 31
	s_lshl_b64 s[14:15], s[12:13], 19
	s_add_u32 s14, s0, s14
	s_addc_u32 s15, s26, s15
	s_and_b64 s[16:17], s[8:9], exec
	s_cselect_b32 s13, s15, s23
	s_cselect_b32 s40, s14, s22
	s_ashr_i32 s11, s10, 31
	s_lshl_b64 s[16:17], s[10:11], 19
	s_add_u32 s16, s27, s16
	s_addc_u32 s17, s28, s17
	s_and_b64 s[24:25], s[8:9], exec
	s_cselect_b32 s11, s17, s21
	s_cselect_b32 s41, s16, s20
	s_add_u32 s42, s20, 0x100
	s_addc_u32 s43, s21, 0
	s_add_u32 s20, s22, 0x40080
	v_mov_b32_e32 v0, 0
	s_addc_u32 s21, s23, 0
	s_mov_b32 s45, -2
	v_mov_b64_e32 v[0:1], 0
	v_mov_b64_e32 v[2:3], 0
	v_mov_b64_e32 v[4:5], 0
	v_mov_b64_e32 v[6:7], 0
	v_mov_b64_e32 v[16:17], 0
	v_mov_b64_e32 v[18:19], 0
	v_mov_b64_e32 v[20:21], 0
	v_mov_b64_e32 v[22:23], 0
	v_mov_b64_e32 v[32:33], 0
	v_mov_b64_e32 v[34:35], 0
	v_mov_b64_e32 v[36:37], 0
	v_mov_b64_e32 v[38:39], 0
	v_mov_b64_e32 v[48:49], 0
	v_mov_b64_e32 v[50:51], 0
	v_mov_b64_e32 v[52:53], 0
	v_mov_b64_e32 v[54:55], 0
	v_mov_b64_e32 v[8:9], 0
	v_mov_b64_e32 v[10:11], 0
	v_mov_b64_e32 v[12:13], 0
	v_mov_b64_e32 v[14:15], 0
	v_mov_b64_e32 v[24:25], 0
	v_mov_b64_e32 v[26:27], 0
	v_mov_b64_e32 v[28:29], 0
	v_mov_b64_e32 v[30:31], 0
	v_mov_b64_e32 v[40:41], 0
	v_mov_b64_e32 v[42:43], 0
	v_mov_b64_e32 v[44:45], 0
	v_mov_b64_e32 v[46:47], 0
	v_mov_b64_e32 v[56:57], 0
	v_mov_b64_e32 v[58:59], 0
	v_mov_b64_e32 v[60:61], 0
	v_mov_b64_e32 v[62:63], 0
	v_mov_b64_e32 v[64:65], 0
	v_mov_b64_e32 v[66:67], 0
	v_mov_b64_e32 v[68:69], 0
	v_mov_b64_e32 v[70:71], 0
	v_mov_b64_e32 v[80:81], 0
	v_mov_b64_e32 v[82:83], 0
	v_mov_b64_e32 v[84:85], 0
	v_mov_b64_e32 v[86:87], 0
	v_mov_b64_e32 v[96:97], 0
	v_mov_b64_e32 v[98:99], 0
	v_mov_b64_e32 v[100:101], 0
	v_mov_b64_e32 v[102:103], 0
	v_mov_b64_e32 v[112:113], 0
	v_mov_b64_e32 v[114:115], 0
	v_mov_b64_e32 v[116:117], 0
	v_mov_b64_e32 v[118:119], 0
	v_mov_b64_e32 v[72:73], 0
	v_mov_b64_e32 v[74:75], 0
	v_mov_b64_e32 v[76:77], 0
	v_mov_b64_e32 v[78:79], 0
	v_mov_b64_e32 v[88:89], 0
	v_mov_b64_e32 v[90:91], 0
	v_mov_b64_e32 v[92:93], 0
	v_mov_b64_e32 v[94:95], 0
	v_mov_b64_e32 v[104:105], 0
	v_mov_b64_e32 v[106:107], 0
	v_mov_b64_e32 v[108:109], 0
	v_mov_b64_e32 v[110:111], 0
	v_mov_b64_e32 v[120:121], 0
	v_mov_b64_e32 v[122:123], 0
	v_mov_b64_e32 v[124:125], 0
	v_mov_b64_e32 v[126:127], 0
	s_mov_b64 s[50:51], 0x80
	s_add_u32 s22, s20, 0xfffc0080
	s_addc_u32 s23, s21, -1
	s_add_i32 s46, 0, 0x10000
	s_cmp_eq_u32 s45, 12
	s_cselect_b32 s25, s13, s23
	s_cselect_b32 s24, s40, s22
	s_cselect_b32 s23, s11, s43
	s_cselect_b32 s22, s41, s42
	s_add_i32 s48, 0, 0x14000
	v_add_u32_e32 v164, s46, v143
	v_add_u32_e32 v180, s48, v143
.LBB0_539:
	ds_read_b128 v[138:141], v164
	ds_read_b128 v[156:159], v164 offset:1024
	ds_read_b128 v[160:163], v164 offset:2048
	ds_read_b128 v[164:167], v164 offset:3072
	ds_read_b128 v[168:171], v180
	ds_read_b128 v[172:175], v180 offset:1024
	ds_read_b128 v[176:179], v180 offset:2048
	ds_read_b128 v[180:183], v180 offset:3072
	v_lshl_add_u64 v[214:215], s[20:21], 0, v[136:137]
	s_add_i32 m0, s30, 0xc000
	ds_read_b128 v[184:187], v155
	ds_read_b128 v[188:191], v155 offset:1024
	ds_read_b128 v[192:195], v155 offset:2048
	ds_read_b128 v[196:199], v155 offset:3072
	ds_read_b128 v[200:203], v155 offset:4096
	ds_read_b128 v[204:207], v155 offset:5120
	ds_read_b128 v[208:211], v155 offset:6144
	ds_read_b128 v[234:237], v155 offset:7168
	global_load_lds_dwordx4 v[214:215], off
	v_lshl_add_u64 v[214:215], s[20:21], 0, v[134:135]
	s_add_i32 m0, s30, 0xe000
	s_nop 0
	global_load_lds_dwordx4 v[214:215], off
	s_waitcnt vmcnt(8)
	s_waitcnt lgkmcnt(0)
	s_barrier
	s_setprio 1
	s_waitcnt lgkmcnt(0)
	v_mfma_f32_16x16x32_bf16 v[124:127], v[138:141], v[184:187], v[124:127]
	v_mfma_f32_16x16x32_bf16 v[120:123], v[160:163], v[184:187], v[120:123]
	v_mfma_f32_16x16x32_bf16 v[108:111], v[138:141], v[192:195], v[108:111]
	v_mfma_f32_16x16x32_bf16 v[104:107], v[160:163], v[192:195], v[104:107]
	v_mfma_f32_16x16x32_bf16 v[92:95], v[138:141], v[200:203], v[92:95]
	v_mfma_f32_16x16x32_bf16 v[88:91], v[160:163], v[200:203], v[88:91]
	v_mfma_f32_16x16x32_bf16 v[76:79], v[138:141], v[208:211], v[76:79]
	v_mfma_f32_16x16x32_bf16 v[72:75], v[160:163], v[208:211], v[72:75]
	v_mfma_f32_16x16x32_bf16 v[124:127], v[156:159], v[188:191], v[124:127]
	v_mfma_f32_16x16x32_bf16 v[120:123], v[164:167], v[188:191], v[120:123]
	v_mfma_f32_16x16x32_bf16 v[108:111], v[156:159], v[196:199], v[108:111]
	v_mfma_f32_16x16x32_bf16 v[104:107], v[164:167], v[196:199], v[104:107]
	v_mfma_f32_16x16x32_bf16 v[92:95], v[156:159], v[204:207], v[92:95]
	v_mfma_f32_16x16x32_bf16 v[88:91], v[164:167], v[204:207], v[88:91]
	v_mfma_f32_16x16x32_bf16 v[76:79], v[156:159], v[234:237], v[76:79]
	v_mfma_f32_16x16x32_bf16 v[72:75], v[164:167], v[234:237], v[72:75]
	s_setprio 0
	s_setprio 1
	v_mfma_f32_16x16x32_bf16 v[116:119], v[168:171], v[184:187], v[116:119]
	v_mfma_f32_16x16x32_bf16 v[112:115], v[176:179], v[184:187], v[112:115]
	v_mfma_f32_16x16x32_bf16 v[100:103], v[168:171], v[192:195], v[100:103]
	v_mfma_f32_16x16x32_bf16 v[96:99], v[176:179], v[192:195], v[96:99]
	v_mfma_f32_16x16x32_bf16 v[84:87], v[168:171], v[200:203], v[84:87]
	v_mfma_f32_16x16x32_bf16 v[80:83], v[176:179], v[200:203], v[80:83]
	v_mfma_f32_16x16x32_bf16 v[68:71], v[168:171], v[208:211], v[68:71]
	v_mfma_f32_16x16x32_bf16 v[64:67], v[176:179], v[208:211], v[64:67]
	v_mfma_f32_16x16x32_bf16 v[116:119], v[172:175], v[188:191], v[116:119]
	v_mfma_f32_16x16x32_bf16 v[112:115], v[180:183], v[188:191], v[112:115]
	v_mfma_f32_16x16x32_bf16 v[100:103], v[172:175], v[196:199], v[100:103]
	v_mfma_f32_16x16x32_bf16 v[96:99], v[180:183], v[196:199], v[96:99]
	v_mfma_f32_16x16x32_bf16 v[84:87], v[172:175], v[204:207], v[84:87]
	v_mfma_f32_16x16x32_bf16 v[80:83], v[180:183], v[204:207], v[80:83]
	v_mfma_f32_16x16x32_bf16 v[68:71], v[172:175], v[234:237], v[68:71]
	v_mfma_f32_16x16x32_bf16 v[64:67], v[180:183], v[234:237], v[64:67]
	s_setprio 0
	s_barrier
; #define PG8_STAGE(bufoff, gbase, voff) do { _Pragma("unroll") for (int _i = 0; _i < 2; ++_i) \
;         __builtin_amdgcn_global_load_lds((const unsigned*)((const char*)(gbase) + (voff)[_i]), (PG8_LAS unsigned*)(lds + (bufoff) + ldsw + _i * 8192), 16, 0, 0); } while (0)
; #define PG8_LDA(dst, b, h) do { _Pragma("unroll") for (int m = 0; m < 4; ++m) _Pragma("unroll") for (int k = 0; k < 2; ++k) dst[m][k] = *(const PG8_LAS bf16x8*)(lds + PG8_SA(b, h) + aoff + m * 2048 + k * 1024); } while (0)
; #define PG8_LDB(dst, b, h) do { _Pragma("unroll") for (int n = 0; n < 2; ++n) _Pragma("unroll") for (int k = 0; k < 2; ++k) dst[n][k] = *(const PG8_LAS bf16x8*)(lds + PG8_SB(b, h) + boff + n * 2048 + k * 1024); } while (0)
; #define PG8_MMA(ai, bj, At, Bt) do { __builtin_amdgcn_s_setprio(1); _Pragma("unroll") for (int m = 0; m < 4; ++m) _Pragma("unroll") for (int n = 0; n < 2; ++n) _Pragma("unroll") for (int k = 0; k < 2; ++k) \
;         acc[ai][bj][m][n] = __builtin_amdgcn_mfma_f32_16x16x32_bf16(Bt[n][k], At[m][k], acc[ai][bj][m][n], 0, 0, 0); __builtin_amdgcn_s_setprio(0); } while (0)
; #define PG8_WAIT_V(n) asm volatile("s_waitcnt vmcnt(" #n ")" ::: "memory")
; #define PG8_WAIT_L(n) asm volatile("s_waitcnt lgkmcnt(" #n ")" ::: "memory")
; #define PG8_BAR __builtin_amdgcn_s_barrier()
; #define PG8_SCHED __builtin_amdgcn_sched_barrier(0)
; template <class Epi, class Sched, bool ALIGN_EPI = false, bool SP2 = false>
; __device__ __forceinline__ void gemm_phase(PG8_LAS unsigned char* lds, const Gemm g, const Sched& S, const Epi& E) {
;     ...
;             PG8_LDB(B0, 0, 0); PG8_LDB(B1, 0, 1); PG8_SCHED; PG8_LDA(At, 0, 0); PG8_STAGE(PG8_SA(1, 1), a1 + hstep, voffA);
;             PG8_WAIT_V(8); PG8_WAIT_L(0); PG8_BAR; PG8_MMA(0, 0, At, B0); PG8_MMA(0, 1, At, B1); PG8_BAR; PG8_SCHED;
;             PG8_LDA(At, 0, 1); PG8_STAGE(PG8_SB(0, 0), b2, voffB); PG8_STAGE(PG8_SB(0, 1), b2 + hstep, voffB); PG8_STAGE(PG8_SA(0, 0), a2, voffA);
;             PG8_WAIT_V(8); PG8_WAIT_L(0); PG8_BAR; PG8_MMA(1, 0, At, B0); PG8_MMA(1, 1, At, B1); PG8_BAR; PG8_SCHED;
;             PG8_LDB(B0, 1, 0); PG8_LDB(B1, 1, 1); PG8_SCHED; PG8_LDA(At, 1, 0); PG8_STAGE(PG8_SA(0, 1), a2 + hstep, voffA);
;             PG8_WAIT_V(8); PG8_WAIT_L(0); PG8_BAR; PG8_MMA(0, 0, At, B0); PG8_MMA(0, 1, At, B1); PG8_BAR; PG8_SCHED;
	s_add_i32 s46, s46, s29
	v_lshl_add_u64 v[214:215], s[22:23], 0, v[144:145]
	s_mov_b32 m0, s46
	ds_read_b128 v[184:187], v155 offset:16384
	ds_read_b128 v[188:191], v155 offset:17408
	ds_read_b128 v[192:195], v155 offset:18432
	ds_read_b128 v[196:199], v155 offset:19456
	ds_read_b128 v[200:203], v155 offset:20480
	ds_read_b128 v[204:207], v155 offset:21504
	ds_read_b128 v[208:211], v155 offset:22528
	ds_read_b128 v[234:237], v155 offset:23552
	global_load_lds_dwordx4 v[214:215], off
	s_add_i32 m0, s46, 0x2000
	s_add_u32 s46, s22, 0x40000
	v_lshl_add_u64 v[238:239], s[22:23], 0, v[128:129]
	s_addc_u32 s47, s23, 0
	s_add_i32 s48, s48, s29
	global_load_lds_dwordx4 v[238:239], off
	v_lshl_add_u64 v[244:245], s[46:47], 0, v[144:145]
	s_mov_b32 m0, s48
	v_lshl_add_u64 v[246:247], s[24:25], 0, v[130:131]
	global_load_lds_dwordx4 v[244:245], off
	v_lshl_add_u64 v[244:245], s[46:47], 0, v[128:129]
	s_add_i32 m0, s48, 0x2000
	s_nop 0
	global_load_lds_dwordx4 v[244:245], off
	v_lshl_add_u64 v[244:245], s[24:25], 0, v[132:133]
	s_mov_b32 m0, s30
	s_nop 0
	global_load_lds_dwordx4 v[244:245], off
	s_mov_b32 m0, s31
	s_nop 0
	global_load_lds_dwordx4 v[246:247], off
	s_waitcnt vmcnt(8)
	s_waitcnt lgkmcnt(0)
	s_barrier
	s_setprio 1
	s_waitcnt lgkmcnt(0)
	v_mfma_f32_16x16x32_bf16 v[60:63], v[138:141], v[184:187], v[60:63]
	v_mfma_f32_16x16x32_bf16 v[56:59], v[160:163], v[184:187], v[56:59]
	v_mfma_f32_16x16x32_bf16 v[44:47], v[138:141], v[192:195], v[44:47]
	v_mfma_f32_16x16x32_bf16 v[40:43], v[160:163], v[192:195], v[40:43]
	v_mfma_f32_16x16x32_bf16 v[28:31], v[138:141], v[200:203], v[28:31]
	v_mfma_f32_16x16x32_bf16 v[24:27], v[160:163], v[200:203], v[24:27]
	v_mfma_f32_16x16x32_bf16 v[12:15], v[138:141], v[208:211], v[12:15]
	v_mfma_f32_16x16x32_bf16 v[8:11], v[160:163], v[208:211], v[8:11]
	v_mfma_f32_16x16x32_bf16 v[60:63], v[156:159], v[188:191], v[60:63]
	v_mfma_f32_16x16x32_bf16 v[56:59], v[164:167], v[188:191], v[56:59]
	v_mfma_f32_16x16x32_bf16 v[44:47], v[156:159], v[196:199], v[44:47]
	v_mfma_f32_16x16x32_bf16 v[40:43], v[164:167], v[196:199], v[40:43]
	v_mfma_f32_16x16x32_bf16 v[28:31], v[156:159], v[204:207], v[28:31]
	v_mfma_f32_16x16x32_bf16 v[24:27], v[164:167], v[204:207], v[24:27]
	v_mfma_f32_16x16x32_bf16 v[12:15], v[156:159], v[234:237], v[12:15]
	v_mfma_f32_16x16x32_bf16 v[8:11], v[164:167], v[234:237], v[8:11]
	s_setprio 0
	s_setprio 1
	v_mfma_f32_16x16x32_bf16 v[52:55], v[168:171], v[184:187], v[52:55]
	v_mfma_f32_16x16x32_bf16 v[48:51], v[176:179], v[184:187], v[48:51]
	v_mfma_f32_16x16x32_bf16 v[36:39], v[168:171], v[192:195], v[36:39]
	v_mfma_f32_16x16x32_bf16 v[32:35], v[176:179], v[192:195], v[32:35]
	v_mfma_f32_16x16x32_bf16 v[20:23], v[168:171], v[200:203], v[20:23]
	v_mfma_f32_16x16x32_bf16 v[16:19], v[176:179], v[200:203], v[16:19]
	v_mfma_f32_16x16x32_bf16 v[4:7], v[168:171], v[208:211], v[4:7]
	v_mfma_f32_16x16x32_bf16 v[0:3], v[176:179], v[208:211], v[0:3]
	v_mfma_f32_16x16x32_bf16 v[52:55], v[172:175], v[188:191], v[52:55]
	v_mfma_f32_16x16x32_bf16 v[48:51], v[180:183], v[188:191], v[48:51]
	v_mfma_f32_16x16x32_bf16 v[36:39], v[172:175], v[196:199], v[36:39]
	v_mfma_f32_16x16x32_bf16 v[32:35], v[180:183], v[196:199], v[32:35]
	v_mfma_f32_16x16x32_bf16 v[20:23], v[172:175], v[204:207], v[20:23]
	v_mfma_f32_16x16x32_bf16 v[16:19], v[180:183], v[204:207], v[16:19]
	v_mfma_f32_16x16x32_bf16 v[4:7], v[172:175], v[234:237], v[4:7]
	v_mfma_f32_16x16x32_bf16 v[0:3], v[180:183], v[234:237], v[0:3]
	s_setprio 0
	s_barrier
	s_add_i32 s46, 0, 0x18000
	s_add_i32 s47, 0, 0x1c000
	v_add_u32_e32 v164, s46, v143
	v_add_u32_e32 v180, s47, v143
	ds_read_b128 v[138:141], v164
	ds_read_b128 v[156:159], v164 offset:1024
	ds_read_b128 v[160:163], v164 offset:2048
	ds_read_b128 v[164:167], v164 offset:3072
	ds_read_b128 v[168:171], v180
	ds_read_b128 v[172:175], v180 offset:1024
	ds_read_b128 v[176:179], v180 offset:2048
	ds_read_b128 v[180:183], v180 offset:3072
	s_add_u32 s24, s24, 0x40000
	s_addc_u32 s25, s25, 0
	s_mov_b32 m0, s34
	v_lshl_add_u64 v[248:249], s[24:25], 0, v[132:133]
	ds_read_b128 v[184:187], v155 offset:32768
	ds_read_b128 v[188:191], v155 offset:33792
	ds_read_b128 v[192:195], v155 offset:34816
	ds_read_b128 v[196:199], v155 offset:35840
	ds_read_b128 v[200:203], v155 offset:36864
	ds_read_b128 v[204:207], v155 offset:37888
	ds_read_b128 v[208:211], v155 offset:38912
	ds_read_b128 v[234:237], v155 offset:39936
	global_load_lds_dwordx4 v[248:249], off
	v_lshl_add_u64 v[248:249], s[24:25], 0, v[130:131]
	s_mov_b32 m0, s35
	s_nop 0
	global_load_lds_dwordx4 v[248:249], off
	s_waitcnt vmcnt(8)
	s_waitcnt lgkmcnt(0)
	s_barrier
; #define PG8_STAGE(bufoff, gbase, voff) do { _Pragma("unroll") for (int _i = 0; _i < 2; ++_i) \
;         __builtin_amdgcn_global_load_lds((const unsigned*)((const char*)(gbase) + (voff)[_i]), (PG8_LAS unsigned*)(lds + (bufoff) + ldsw + _i * 8192), 16, 0, 0); } while (0)
; #define PG8_LDA(dst, b, h) do { _Pragma("unroll") for (int m = 0; m < 4; ++m) _Pragma("unroll") for (int k = 0; k < 2; ++k) dst[m][k] = *(const PG8_LAS bf16x8*)(lds + PG8_SA(b, h) + aoff + m * 2048 + k * 1024); } while (0)
; #define PG8_MMA(ai, bj, At, Bt) do { __builtin_amdgcn_s_setprio(1); _Pragma("unroll") for (int m = 0; m < 4; ++m) _Pragma("unroll") for (int n = 0; n < 2; ++n) _Pragma("unroll") for (int k = 0; k < 2; ++k) \
;         acc[ai][bj][m][n] = __builtin_amdgcn_mfma_f32_16x16x32_bf16(Bt[n][k], At[m][k], acc[ai][bj][m][n], 0, 0, 0); __builtin_amdgcn_s_setprio(0); } while (0)
; #define PG8_WAIT_V(n) asm volatile("s_waitcnt vmcnt(" #n ")" ::: "memory")
; #define PG8_WAIT_L(n) asm volatile("s_waitcnt lgkmcnt(" #n ")" ::: "memory")
; #define PG8_BAR __builtin_amdgcn_s_barrier()
; #define PG8_SCHED __builtin_amdgcn_sched_barrier(0)
; template <class Epi, class Sched, bool ALIGN_EPI = false, bool SP2 = false>
; __device__ __forceinline__ void gemm_phase(PG8_LAS unsigned char* lds, const Gemm g, const Sched& S, const Epi& E) {
;     ...
;         for (int t = 0; t < nt; t += 2) {
;             const bool last = (t == nt - 2);
;             const char* a1 = cA + (size_t)(t + 1) * kstep;
;             const char* a2 = last ? nA : cA + (size_t)(t + 2) * kstep; const char* b2 = last ? nB : cB + (size_t)(t + 2) * kstep;
;             const char* a3 = a2 + kstep; const char* b3 = b2 + kstep;
;     ...
;             PG8_WAIT_V(8); PG8_WAIT_L(0); PG8_BAR; PG8_MMA(0, 0, At, B0); PG8_MMA(0, 1, At, B1); PG8_BAR; PG8_SCHED;
;             PG8_LDA(At, 1, 1); PG8_STAGE(PG8_SB(1, 0), b3, voffB); PG8_STAGE(PG8_SB(1, 1), b3 + hstep, voffB); PG8_STAGE(PG8_SA(1, 0), a3, voffA);
;             PG8_WAIT_V(8); PG8_WAIT_L(0); PG8_BAR; PG8_MMA(1, 0, At, B0); PG8_MMA(1, 1, At, B1); PG8_BAR; PG8_SCHED;
	s_setprio 1
	s_waitcnt lgkmcnt(0)
	v_mfma_f32_16x16x32_bf16 v[124:127], v[138:141], v[184:187], v[124:127]
	v_mfma_f32_16x16x32_bf16 v[120:123], v[160:163], v[184:187], v[120:123]
	v_mfma_f32_16x16x32_bf16 v[108:111], v[138:141], v[192:195], v[108:111]
	v_mfma_f32_16x16x32_bf16 v[104:107], v[160:163], v[192:195], v[104:107]
	v_mfma_f32_16x16x32_bf16 v[92:95], v[138:141], v[200:203], v[92:95]
	v_mfma_f32_16x16x32_bf16 v[88:91], v[160:163], v[200:203], v[88:91]
	v_mfma_f32_16x16x32_bf16 v[76:79], v[138:141], v[208:211], v[76:79]
	v_mfma_f32_16x16x32_bf16 v[72:75], v[160:163], v[208:211], v[72:75]
	v_mfma_f32_16x16x32_bf16 v[124:127], v[156:159], v[188:191], v[124:127]
	v_mfma_f32_16x16x32_bf16 v[120:123], v[164:167], v[188:191], v[120:123]
	v_mfma_f32_16x16x32_bf16 v[108:111], v[156:159], v[196:199], v[108:111]
	v_mfma_f32_16x16x32_bf16 v[104:107], v[164:167], v[196:199], v[104:107]
	v_mfma_f32_16x16x32_bf16 v[92:95], v[156:159], v[204:207], v[92:95]
	v_mfma_f32_16x16x32_bf16 v[88:91], v[164:167], v[204:207], v[88:91]
	v_mfma_f32_16x16x32_bf16 v[76:79], v[156:159], v[234:237], v[76:79]
	v_mfma_f32_16x16x32_bf16 v[72:75], v[164:167], v[234:237], v[72:75]
	s_setprio 0
	s_setprio 1
	v_mfma_f32_16x16x32_bf16 v[116:119], v[168:171], v[184:187], v[116:119]
	v_mfma_f32_16x16x32_bf16 v[112:115], v[176:179], v[184:187], v[112:115]
	v_mfma_f32_16x16x32_bf16 v[100:103], v[168:171], v[192:195], v[100:103]
	v_mfma_f32_16x16x32_bf16 v[96:99], v[176:179], v[192:195], v[96:99]
	v_mfma_f32_16x16x32_bf16 v[84:87], v[168:171], v[200:203], v[84:87]
	v_mfma_f32_16x16x32_bf16 v[80:83], v[176:179], v[200:203], v[80:83]
	v_mfma_f32_16x16x32_bf16 v[68:71], v[168:171], v[208:211], v[68:71]
	v_mfma_f32_16x16x32_bf16 v[64:67], v[176:179], v[208:211], v[64:67]
	v_mfma_f32_16x16x32_bf16 v[116:119], v[172:175], v[188:191], v[116:119]
	v_mfma_f32_16x16x32_bf16 v[112:115], v[180:183], v[188:191], v[112:115]
	v_mfma_f32_16x16x32_bf16 v[100:103], v[172:175], v[196:199], v[100:103]
	v_mfma_f32_16x16x32_bf16 v[96:99], v[180:183], v[196:199], v[96:99]
	v_mfma_f32_16x16x32_bf16 v[84:87], v[172:175], v[204:207], v[84:87]
	v_mfma_f32_16x16x32_bf16 v[80:83], v[180:183], v[204:207], v[80:83]
	v_mfma_f32_16x16x32_bf16 v[68:71], v[172:175], v[234:237], v[68:71]
	v_mfma_f32_16x16x32_bf16 v[64:67], v[180:183], v[234:237], v[64:67]
	s_setprio 0
	s_barrier
	s_add_i32 s24, s46, s29
	v_lshl_add_u64 v[214:215], v[214:215], 0, s[50:51]
	s_mov_b32 m0, s24
	ds_read_b128 v[184:187], v155 offset:49152
	ds_read_b128 v[188:191], v155 offset:50176
	ds_read_b128 v[192:195], v155 offset:51200
	ds_read_b128 v[196:199], v155 offset:52224
	ds_read_b128 v[200:203], v155 offset:53248
	ds_read_b128 v[204:207], v155 offset:54272
	ds_read_b128 v[208:211], v155 offset:55296
	ds_read_b128 v[234:237], v155 offset:56320
	global_load_lds_dwordx4 v[214:215], off
	s_add_i32 m0, s24, 0x2000
	s_add_u32 s22, s22, 0x40080
	v_lshl_add_u64 v[214:215], v[238:239], 0, s[50:51]
	s_addc_u32 s23, s23, 0
	s_add_i32 s24, s47, s29
	global_load_lds_dwordx4 v[214:215], off
	v_lshl_add_u64 v[214:215], s[22:23], 0, v[144:145]
	s_mov_b32 m0, s24
	s_nop 0
	global_load_lds_dwordx4 v[214:215], off
	v_lshl_add_u64 v[214:215], s[22:23], 0, v[128:129]
	s_add_i32 m0, s24, 0x2000
	s_nop 0
	global_load_lds_dwordx4 v[214:215], off
	v_lshl_add_u64 v[214:215], v[244:245], 0, s[50:51]
	s_mov_b32 m0, s33
	s_nop 0
	global_load_lds_dwordx4 v[214:215], off
	v_lshl_add_u64 v[214:215], v[246:247], 0, s[50:51]
	s_mov_b32 m0, s36
	s_nop 0
	global_load_lds_dwordx4 v[214:215], off
	s_waitcnt vmcnt(8)
	s_waitcnt lgkmcnt(0)
	s_barrier
	s_setprio 1
	s_waitcnt lgkmcnt(0)
	v_mfma_f32_16x16x32_bf16 v[60:63], v[138:141], v[184:187], v[60:63]
	v_mfma_f32_16x16x32_bf16 v[56:59], v[160:163], v[184:187], v[56:59]
	v_mfma_f32_16x16x32_bf16 v[44:47], v[138:141], v[192:195], v[44:47]
	v_mfma_f32_16x16x32_bf16 v[40:43], v[160:163], v[192:195], v[40:43]
	v_mfma_f32_16x16x32_bf16 v[28:31], v[138:141], v[200:203], v[28:31]
	v_mfma_f32_16x16x32_bf16 v[24:27], v[160:163], v[200:203], v[24:27]
	v_mfma_f32_16x16x32_bf16 v[12:15], v[138:141], v[208:211], v[12:15]
	v_mfma_f32_16x16x32_bf16 v[8:11], v[160:163], v[208:211], v[8:11]
	v_mfma_f32_16x16x32_bf16 v[60:63], v[156:159], v[188:191], v[60:63]
	v_mfma_f32_16x16x32_bf16 v[56:59], v[164:167], v[188:191], v[56:59]
	v_mfma_f32_16x16x32_bf16 v[44:47], v[156:159], v[196:199], v[44:47]
	v_mfma_f32_16x16x32_bf16 v[40:43], v[164:167], v[196:199], v[40:43]
	v_mfma_f32_16x16x32_bf16 v[28:31], v[156:159], v[204:207], v[28:31]
	v_mfma_f32_16x16x32_bf16 v[24:27], v[164:167], v[204:207], v[24:27]
	v_mfma_f32_16x16x32_bf16 v[12:15], v[156:159], v[234:237], v[12:15]
	v_mfma_f32_16x16x32_bf16 v[8:11], v[164:167], v[234:237], v[8:11]
	s_setprio 0
	s_setprio 1
	v_mfma_f32_16x16x32_bf16 v[52:55], v[168:171], v[184:187], v[52:55]
	v_mfma_f32_16x16x32_bf16 v[48:51], v[176:179], v[184:187], v[48:51]
	v_mfma_f32_16x16x32_bf16 v[36:39], v[168:171], v[192:195], v[36:39]
	v_mfma_f32_16x16x32_bf16 v[32:35], v[176:179], v[192:195], v[32:35]
	v_mfma_f32_16x16x32_bf16 v[20:23], v[168:171], v[200:203], v[20:23]
	v_mfma_f32_16x16x32_bf16 v[16:19], v[176:179], v[200:203], v[16:19]
	v_mfma_f32_16x16x32_bf16 v[4:7], v[168:171], v[208:211], v[4:7]
	v_mfma_f32_16x16x32_bf16 v[0:3], v[176:179], v[208:211], v[0:3]
	v_mfma_f32_16x16x32_bf16 v[52:55], v[172:175], v[188:191], v[52:55]
	v_mfma_f32_16x16x32_bf16 v[48:51], v[180:183], v[188:191], v[48:51]
	v_mfma_f32_16x16x32_bf16 v[36:39], v[172:175], v[196:199], v[36:39]
	v_mfma_f32_16x16x32_bf16 v[32:35], v[180:183], v[196:199], v[32:35]
	v_mfma_f32_16x16x32_bf16 v[20:23], v[172:175], v[204:207], v[20:23]
	v_mfma_f32_16x16x32_bf16 v[16:19], v[180:183], v[204:207], v[16:19]
	v_mfma_f32_16x16x32_bf16 v[4:7], v[172:175], v[234:237], v[4:7]
	v_mfma_f32_16x16x32_bf16 v[0:3], v[180:183], v[234:237], v[0:3]
	s_setprio 0
	s_add_i32 s45, s45, 2
	s_add_u32 s42, s42, 0x100
	s_addc_u32 s43, s43, 0
	s_add_u32 s20, s20, 0x100
	s_addc_u32 s21, s21, 0
	s_add_u32 s22, s20, 0xfffc0080
	s_addc_u32 s23, s21, -1
	s_add_i32 s46, 0, 0x10000
	s_cmp_eq_u32 s45, 12
	s_cselect_b32 s25, s13, s23
	s_cselect_b32 s24, s40, s22
	s_cselect_b32 s23, s11, s43
	s_cselect_b32 s22, s41, s42
	s_add_i32 s48, 0, 0x14000
	v_add_u32_e32 v164, s46, v143
	v_add_u32_e32 v180, s48, v143
	s_barrier
	s_cmp_gt_u32 s45, 13
	s_cbranch_scc0 .LBB0_539
	s_and_b64 vcc, exec, s[6:7]
	s_cbranch_vccz .LBB0_542
	s_barrier

; #define PG8_STAGE(bufoff, gbase, voff) do { _Pragma("unroll") for (int _i = 0; _i < 2; ++_i) \
;         __builtin_amdgcn_global_load_lds((const unsigned*)((const char*)(gbase) + (voff)[_i]), (PG8_LAS unsigned*)(lds + (bufoff) + ldsw + _i * 8192), 16, 0, 0); } while (0)
; #define PG8_LDA(dst, b, h) do { _Pragma("unroll") for (int m = 0; m < 4; ++m) _Pragma("unroll") for (int k = 0; k < 2; ++k) dst[m][k] = *(const PG8_LAS bf16x8*)(lds + PG8_SA(b, h) + aoff + m * 2048 + k * 1024); } while (0)
; #define PG8_LDB(dst, b, h) do { _Pragma("unroll") for (int n = 0; n < 2; ++n) _Pragma("unroll") for (int k = 0; k < 2; ++k) dst[n][k] = *(const PG8_LAS bf16x8*)(lds + PG8_SB(b, h) + boff + n * 2048 + k * 1024); } while (0)
; #define PG8_WAIT_V(n) asm volatile("s_waitcnt vmcnt(" #n ")" ::: "memory")
; #define PG8_BAR __builtin_amdgcn_s_barrier()
; template <class Epi, class Sched, bool ALIGN_EPI = false, bool SP2 = false>
; __device__ __forceinline__ void gemm_phase(PG8_LAS unsigned char* lds, const Gemm g, const Sched& S, const Epi& E) {
;     ...
;         const bool has_next = S.next(ui + 1, nxt);
;         const char* nA = has_next ? (const char*)g.A + (size_t)nxt.pm * tstep + (size_t)nxt.kt0 * kstep : cA; const char* nB = has_next ? (const char*)g.Bt + (size_t)nxt.pn * tstep + (size_t)nxt.kt0 * kstep : cB;
;         const int nt = cur.nkt;
;         for (int t = 0; t < nt; t += 2) {
;             const bool last = (t == nt - 2);
;             const char* a1 = cA + (size_t)(t + 1) * kstep;
;             const char* a2 = last ? nA : cA + (size_t)(t + 2) * kstep; const char* b2 = last ? nB : cB + (size_t)(t + 2) * kstep;
;             const char* a3 = a2 + kstep; const char* b3 = b2 + kstep;
;             if (last && has_next) S.a_ready(nxt);
;             if constexpr (SP2) {
;             PG8_LDB(B0, 0, 0); PG8_LDB(B1, 0, 1); PG8_SCHED; PG8_LDA(At, 0, 0); PG8_STAGE(PG8_SA(1, 1), a1 + hstep, voffA);
;             PG8_WAIT_V(8); PG8_WAIT_L(0); PG8_BAR; PG8_MMA(0, 0, At, B0); PG8_MMA(0, 1, At, B1); PG8_BAR; PG8_SCHED;
;     ...
; #pragma unroll
;         for (int a = 0; a < 2; ++a)
; #pragma unroll
;             for (int b = 0; b < 2; ++b)
; #pragma unroll
;                 for (int m = 0; m < 4; ++m)
; #pragma unroll
;                     for (int n = 0; n < 2; ++n) acc[a][b][m][n] = (f32x4){0.f, 0.f, 0.f, 0.f};
;         cur = nxt; cA = nA; cB = nB; ++ui;
.LBB0_1204:
	s_ashr_i32 s17, s16, 31
	s_lshl_b64 s[18:19], s[16:17], 19
	s_add_u32 s18, s44, s18
	s_addc_u32 s19, s45, s19
	s_and_b64 s[20:21], s[12:13], exec
	s_cselect_b32 s17, s19, s29
	s_cselect_b32 s23, s18, s28
	s_ashr_i32 s15, s14, 31
	s_lshl_b64 s[20:21], s[14:15], 19
	s_add_u32 s20, s46, s20
	s_addc_u32 s21, s47, s21
	s_and_b64 s[30:31], s[12:13], exec
	s_cselect_b32 s15, s21, s27
	s_cselect_b32 s42, s20, s26
	s_add_u32 s43, s26, 0x100
	s_addc_u32 s48, s27, 0
	s_add_u32 s26, s28, 0x40080
	v_mov_b32_e32 v0, 0
	s_addc_u32 s27, s29, 0
	s_mov_b32 s49, -2
	s_waitcnt lgkmcnt(0)
	v_mov_b64_e32 v[0:1], 0
	v_mov_b64_e32 v[2:3], 0
	v_mov_b64_e32 v[4:5], 0
	v_mov_b64_e32 v[6:7], 0
	v_mov_b64_e32 v[16:17], 0
	v_mov_b64_e32 v[18:19], 0
	v_mov_b64_e32 v[20:21], 0
	v_mov_b64_e32 v[22:23], 0
	v_mov_b64_e32 v[32:33], 0
	v_mov_b64_e32 v[34:35], 0
	v_mov_b64_e32 v[36:37], 0
	v_mov_b64_e32 v[38:39], 0
	v_mov_b64_e32 v[48:49], 0
	v_mov_b64_e32 v[50:51], 0
	v_mov_b64_e32 v[52:53], 0
	v_mov_b64_e32 v[54:55], 0
	v_mov_b64_e32 v[8:9], 0
	v_mov_b64_e32 v[10:11], 0
	v_mov_b64_e32 v[12:13], 0
	v_mov_b64_e32 v[14:15], 0
	v_mov_b64_e32 v[24:25], 0
	v_mov_b64_e32 v[26:27], 0
	v_mov_b64_e32 v[28:29], 0
	v_mov_b64_e32 v[30:31], 0
	v_mov_b64_e32 v[40:41], 0
	v_mov_b64_e32 v[42:43], 0
	v_mov_b64_e32 v[44:45], 0
	v_mov_b64_e32 v[46:47], 0
	v_mov_b64_e32 v[56:57], 0
	v_mov_b64_e32 v[58:59], 0
	v_mov_b64_e32 v[60:61], 0
	v_mov_b64_e32 v[62:63], 0
	v_mov_b64_e32 v[64:65], 0
	v_mov_b64_e32 v[66:67], 0
	v_mov_b64_e32 v[68:69], 0
	v_mov_b64_e32 v[70:71], 0
	v_mov_b64_e32 v[80:81], 0
	v_mov_b64_e32 v[82:83], 0
	v_mov_b64_e32 v[84:85], 0
	v_mov_b64_e32 v[86:87], 0
	v_mov_b64_e32 v[96:97], 0
	v_mov_b64_e32 v[98:99], 0
	v_mov_b64_e32 v[100:101], 0
	v_mov_b64_e32 v[102:103], 0
	v_mov_b64_e32 v[112:113], 0
	v_mov_b64_e32 v[114:115], 0
	v_mov_b64_e32 v[116:117], 0
	v_mov_b64_e32 v[118:119], 0
	v_mov_b64_e32 v[72:73], 0
	v_mov_b64_e32 v[74:75], 0
	v_mov_b64_e32 v[76:77], 0
	v_mov_b64_e32 v[78:79], 0
	v_mov_b64_e32 v[88:89], 0
	v_mov_b64_e32 v[90:91], 0
	v_mov_b64_e32 v[92:93], 0
	v_mov_b64_e32 v[94:95], 0
	v_mov_b64_e32 v[104:105], 0
	v_mov_b64_e32 v[106:107], 0
	v_mov_b64_e32 v[108:109], 0
	v_mov_b64_e32 v[110:111], 0
	v_mov_b64_e32 v[120:121], 0
	s_waitcnt vmcnt(0)
	v_mov_b32_e32 v122, v0
	v_mov_b32_e32 v123, v0
	v_mov_b32_e32 v124, v0
	v_mov_b32_e32 v125, v0
	v_mov_b32_e32 v126, v0
	v_mov_b32_e32 v127, v0
	s_mov_b64 s[54:55], 0x80
	s_add_u32 s28, s26, 0xfffc0080
	s_addc_u32 s29, s27, -1
	s_add_i32 s50, 0, 0x10000
	s_cmp_eq_u32 s49, 12
	s_cselect_b32 s31, s17, s29
	s_cselect_b32 s30, s23, s28
	v_add_u32_e32 v142, s50, v157
	s_cselect_b32 s29, s15, s48
	s_cselect_b32 s28, s42, s43
	s_add_i32 s52, 0, 0x14000
.LBB0_1205:
	ds_read_b128 v[138:141], v142
	ds_read_b128 v[160:163], v142 offset:1024
	ds_read_b128 v[164:167], v142 offset:2048
	ds_read_b128 v[168:171], v142 offset:3072
	v_add_u32_e32 v142, s52, v157
	ds_read_b128 v[172:175], v142
	ds_read_b128 v[176:179], v142 offset:1024
	ds_read_b128 v[180:183], v142 offset:2048
	ds_read_b128 v[184:187], v142 offset:3072
	v_lshl_add_u64 v[142:143], s[26:27], 0, v[136:137]
	s_add_i32 m0, s25, 0xc000
	ds_read_b128 v[188:191], v159
	ds_read_b128 v[192:195], v159 offset:1024
	ds_read_b128 v[196:199], v159 offset:2048
	ds_read_b128 v[200:203], v159 offset:3072
	ds_read_b128 v[204:207], v159 offset:4096
	ds_read_b128 v[208:211], v159 offset:5120
	ds_read_b128 v[234:237], v159 offset:6144
	ds_read_b128 v[244:247], v159 offset:7168
	global_load_lds_dwordx4 v[142:143], off
	v_lshl_add_u64 v[142:143], s[26:27], 0, v[134:135]
	s_add_i32 m0, s25, 0xe000
	s_nop 0
	global_load_lds_dwordx4 v[142:143], off
	s_waitcnt vmcnt(8)
	s_waitcnt lgkmcnt(0)
	s_barrier
	s_setprio 1
	s_waitcnt lgkmcnt(0)
	v_mfma_f32_16x16x32_bf16 v[124:127], v[138:141], v[188:191], v[124:127]
	v_mfma_f32_16x16x32_bf16 v[120:123], v[164:167], v[188:191], v[120:123]
	v_mfma_f32_16x16x32_bf16 v[108:111], v[138:141], v[196:199], v[108:111]
	v_mfma_f32_16x16x32_bf16 v[104:107], v[164:167], v[196:199], v[104:107]
	v_mfma_f32_16x16x32_bf16 v[92:95], v[138:141], v[204:207], v[92:95]
	v_mfma_f32_16x16x32_bf16 v[88:91], v[164:167], v[204:207], v[88:91]
	v_mfma_f32_16x16x32_bf16 v[76:79], v[138:141], v[234:237], v[76:79]
	v_mfma_f32_16x16x32_bf16 v[72:75], v[164:167], v[234:237], v[72:75]
	v_mfma_f32_16x16x32_bf16 v[124:127], v[160:163], v[192:195], v[124:127]
	v_mfma_f32_16x16x32_bf16 v[120:123], v[168:171], v[192:195], v[120:123]
	v_mfma_f32_16x16x32_bf16 v[108:111], v[160:163], v[200:203], v[108:111]
	v_mfma_f32_16x16x32_bf16 v[104:107], v[168:171], v[200:203], v[104:107]
	v_mfma_f32_16x16x32_bf16 v[92:95], v[160:163], v[208:211], v[92:95]
	v_mfma_f32_16x16x32_bf16 v[88:91], v[168:171], v[208:211], v[88:91]
	v_mfma_f32_16x16x32_bf16 v[76:79], v[160:163], v[244:247], v[76:79]
	v_mfma_f32_16x16x32_bf16 v[72:75], v[168:171], v[244:247], v[72:75]
	s_setprio 0
	s_setprio 1
	v_mfma_f32_16x16x32_bf16 v[116:119], v[172:175], v[188:191], v[116:119]
	v_mfma_f32_16x16x32_bf16 v[112:115], v[180:183], v[188:191], v[112:115]
	v_mfma_f32_16x16x32_bf16 v[100:103], v[172:175], v[196:199], v[100:103]
	v_mfma_f32_16x16x32_bf16 v[96:99], v[180:183], v[196:199], v[96:99]
	v_mfma_f32_16x16x32_bf16 v[84:87], v[172:175], v[204:207], v[84:87]
	v_mfma_f32_16x16x32_bf16 v[80:83], v[180:183], v[204:207], v[80:83]
	v_mfma_f32_16x16x32_bf16 v[68:71], v[172:175], v[234:237], v[68:71]
	v_mfma_f32_16x16x32_bf16 v[64:67], v[180:183], v[234:237], v[64:67]
	v_mfma_f32_16x16x32_bf16 v[116:119], v[176:179], v[192:195], v[116:119]
	v_mfma_f32_16x16x32_bf16 v[112:115], v[184:187], v[192:195], v[112:115]
	v_mfma_f32_16x16x32_bf16 v[100:103], v[176:179], v[200:203], v[100:103]
	v_mfma_f32_16x16x32_bf16 v[96:99], v[184:187], v[200:203], v[96:99]
	v_mfma_f32_16x16x32_bf16 v[84:87], v[176:179], v[208:211], v[84:87]
	v_mfma_f32_16x16x32_bf16 v[80:83], v[184:187], v[208:211], v[80:83]
	v_mfma_f32_16x16x32_bf16 v[68:71], v[176:179], v[244:247], v[68:71]
	v_mfma_f32_16x16x32_bf16 v[64:67], v[184:187], v[244:247], v[64:67]
	s_setprio 0
	s_barrier
; #define PG8_STAGE(bufoff, gbase, voff) do { _Pragma("unroll") for (int _i = 0; _i < 2; ++_i) \
;         __builtin_amdgcn_global_load_lds((const unsigned*)((const char*)(gbase) + (voff)[_i]), (PG8_LAS unsigned*)(lds + (bufoff) + ldsw + _i * 8192), 16, 0, 0); } while (0)
; #define PG8_LDA(dst, b, h) do { _Pragma("unroll") for (int m = 0; m < 4; ++m) _Pragma("unroll") for (int k = 0; k < 2; ++k) dst[m][k] = *(const PG8_LAS bf16x8*)(lds + PG8_SA(b, h) + aoff + m * 2048 + k * 1024); } while (0)
; #define PG8_LDB(dst, b, h) do { _Pragma("unroll") for (int n = 0; n < 2; ++n) _Pragma("unroll") for (int k = 0; k < 2; ++k) dst[n][k] = *(const PG8_LAS bf16x8*)(lds + PG8_SB(b, h) + boff + n * 2048 + k * 1024); } while (0)
; #define PG8_MMA(ai, bj, At, Bt) do { __builtin_amdgcn_s_setprio(1); _Pragma("unroll") for (int m = 0; m < 4; ++m) _Pragma("unroll") for (int n = 0; n < 2; ++n) _Pragma("unroll") for (int k = 0; k < 2; ++k) \
;         acc[ai][bj][m][n] = __builtin_amdgcn_mfma_f32_16x16x32_bf16(Bt[n][k], At[m][k], acc[ai][bj][m][n], 0, 0, 0); __builtin_amdgcn_s_setprio(0); } while (0)
; #define PG8_WAIT_V(n) asm volatile("s_waitcnt vmcnt(" #n ")" ::: "memory")
; #define PG8_WAIT_L(n) asm volatile("s_waitcnt lgkmcnt(" #n ")" ::: "memory")
; #define PG8_BAR __builtin_amdgcn_s_barrier()
; #define PG8_SCHED __builtin_amdgcn_sched_barrier(0)
; template <class Epi, class Sched, bool ALIGN_EPI = false, bool SP2 = false>
; __device__ __forceinline__ void gemm_phase(PG8_LAS unsigned char* lds, const Gemm g, const Sched& S, const Epi& E) {
;     ...
;             PG8_LDB(B0, 0, 0); PG8_LDB(B1, 0, 1); PG8_SCHED; PG8_LDA(At, 0, 0); PG8_STAGE(PG8_SA(1, 1), a1 + hstep, voffA);
;             PG8_WAIT_V(8); PG8_WAIT_L(0); PG8_BAR; PG8_MMA(0, 0, At, B0); PG8_MMA(0, 1, At, B1); PG8_BAR; PG8_SCHED;
;             PG8_LDA(At, 0, 1); PG8_STAGE(PG8_SB(0, 0), b2, voffB); PG8_STAGE(PG8_SB(0, 1), b2 + hstep, voffB); PG8_STAGE(PG8_SA(0, 0), a2, voffA);
;             PG8_WAIT_V(8); PG8_WAIT_L(0); PG8_BAR; PG8_MMA(1, 0, At, B0); PG8_MMA(1, 1, At, B1); PG8_BAR; PG8_SCHED;
;             PG8_LDB(B0, 1, 0); PG8_LDB(B1, 1, 1); PG8_SCHED; PG8_LDA(At, 1, 0); PG8_STAGE(PG8_SA(0, 1), a2 + hstep, voffA);
;             PG8_WAIT_V(8); PG8_WAIT_L(0); PG8_BAR; PG8_MMA(0, 0, At, B0); PG8_MMA(0, 1, At, B1); PG8_BAR; PG8_SCHED;
	s_add_i32 s50, s50, s0
	v_lshl_add_u64 v[142:143], s[28:29], 0, v[144:145]
	s_mov_b32 m0, s50
	ds_read_b128 v[188:191], v159 offset:16384
	ds_read_b128 v[192:195], v159 offset:17408
	ds_read_b128 v[196:199], v159 offset:18432
	ds_read_b128 v[200:203], v159 offset:19456
	ds_read_b128 v[204:207], v159 offset:20480
	ds_read_b128 v[208:211], v159 offset:21504
	ds_read_b128 v[234:237], v159 offset:22528
	ds_read_b128 v[244:247], v159 offset:23552
	global_load_lds_dwordx4 v[142:143], off
	s_add_i32 m0, s50, 0x2000
	s_add_u32 s50, s28, 0x40000
	v_lshl_add_u64 v[154:155], s[28:29], 0, v[132:133]
	s_addc_u32 s51, s29, 0
	s_add_i32 s52, s52, s0
	global_load_lds_dwordx4 v[154:155], off
	v_lshl_add_u64 v[214:215], s[50:51], 0, v[144:145]
	s_mov_b32 m0, s52
	v_lshl_add_u64 v[238:239], s[30:31], 0, v[130:131]
	global_load_lds_dwordx4 v[214:215], off
	v_lshl_add_u64 v[214:215], s[50:51], 0, v[132:133]
	s_add_i32 m0, s52, 0x2000
	s_nop 0
	global_load_lds_dwordx4 v[214:215], off
	v_lshl_add_u64 v[214:215], s[30:31], 0, v[128:129]
	s_mov_b32 m0, s25
	s_nop 0
	global_load_lds_dwordx4 v[214:215], off
	s_mov_b32 m0, s34
	s_nop 0
	global_load_lds_dwordx4 v[238:239], off
	s_waitcnt vmcnt(8)
	s_waitcnt lgkmcnt(0)
	s_barrier
	s_setprio 1
	s_waitcnt lgkmcnt(0)
	v_mfma_f32_16x16x32_bf16 v[60:63], v[138:141], v[188:191], v[60:63]
	v_mfma_f32_16x16x32_bf16 v[56:59], v[164:167], v[188:191], v[56:59]
	v_mfma_f32_16x16x32_bf16 v[44:47], v[138:141], v[196:199], v[44:47]
	v_mfma_f32_16x16x32_bf16 v[40:43], v[164:167], v[196:199], v[40:43]
	v_mfma_f32_16x16x32_bf16 v[28:31], v[138:141], v[204:207], v[28:31]
	v_mfma_f32_16x16x32_bf16 v[24:27], v[164:167], v[204:207], v[24:27]
	v_mfma_f32_16x16x32_bf16 v[12:15], v[138:141], v[234:237], v[12:15]
	v_mfma_f32_16x16x32_bf16 v[8:11], v[164:167], v[234:237], v[8:11]
	v_mfma_f32_16x16x32_bf16 v[60:63], v[160:163], v[192:195], v[60:63]
	v_mfma_f32_16x16x32_bf16 v[56:59], v[168:171], v[192:195], v[56:59]
	v_mfma_f32_16x16x32_bf16 v[44:47], v[160:163], v[200:203], v[44:47]
	v_mfma_f32_16x16x32_bf16 v[40:43], v[168:171], v[200:203], v[40:43]
	v_mfma_f32_16x16x32_bf16 v[28:31], v[160:163], v[208:211], v[28:31]
	v_mfma_f32_16x16x32_bf16 v[24:27], v[168:171], v[208:211], v[24:27]
	v_mfma_f32_16x16x32_bf16 v[12:15], v[160:163], v[244:247], v[12:15]
	v_mfma_f32_16x16x32_bf16 v[8:11], v[168:171], v[244:247], v[8:11]
	s_setprio 0
	s_setprio 1
	v_mfma_f32_16x16x32_bf16 v[52:55], v[172:175], v[188:191], v[52:55]
	v_mfma_f32_16x16x32_bf16 v[48:51], v[180:183], v[188:191], v[48:51]
	v_mfma_f32_16x16x32_bf16 v[36:39], v[172:175], v[196:199], v[36:39]
	v_mfma_f32_16x16x32_bf16 v[32:35], v[180:183], v[196:199], v[32:35]
	v_mfma_f32_16x16x32_bf16 v[20:23], v[172:175], v[204:207], v[20:23]
	v_mfma_f32_16x16x32_bf16 v[16:19], v[180:183], v[204:207], v[16:19]
	v_mfma_f32_16x16x32_bf16 v[4:7], v[172:175], v[234:237], v[4:7]
	v_mfma_f32_16x16x32_bf16 v[0:3], v[180:183], v[234:237], v[0:3]
	v_mfma_f32_16x16x32_bf16 v[52:55], v[176:179], v[192:195], v[52:55]
	v_mfma_f32_16x16x32_bf16 v[48:51], v[184:187], v[192:195], v[48:51]
	v_mfma_f32_16x16x32_bf16 v[36:39], v[176:179], v[200:203], v[36:39]
	v_mfma_f32_16x16x32_bf16 v[32:35], v[184:187], v[200:203], v[32:35]
	v_mfma_f32_16x16x32_bf16 v[20:23], v[176:179], v[208:211], v[20:23]
	v_mfma_f32_16x16x32_bf16 v[16:19], v[184:187], v[208:211], v[16:19]
	v_mfma_f32_16x16x32_bf16 v[4:7], v[176:179], v[244:247], v[4:7]
	v_mfma_f32_16x16x32_bf16 v[0:3], v[184:187], v[244:247], v[0:3]
	s_setprio 0
	s_barrier
	s_add_i32 s50, 0, 0x18000
	s_add_i32 s51, 0, 0x1c000
	v_add_u32_e32 v168, s50, v157
	v_add_u32_e32 v184, s51, v157
	ds_read_b128 v[138:141], v168
	ds_read_b128 v[160:163], v168 offset:1024
	ds_read_b128 v[164:167], v168 offset:2048
	ds_read_b128 v[168:171], v168 offset:3072
	ds_read_b128 v[172:175], v184
	ds_read_b128 v[176:179], v184 offset:1024
	ds_read_b128 v[180:183], v184 offset:2048
	ds_read_b128 v[184:187], v184 offset:3072
	s_add_u32 s30, s30, 0x40000
	s_addc_u32 s31, s31, 0
	s_mov_b32 m0, s35
	v_lshl_add_u64 v[248:249], s[30:31], 0, v[128:129]
	ds_read_b128 v[188:191], v159 offset:32768
	ds_read_b128 v[192:195], v159 offset:33792
	ds_read_b128 v[196:199], v159 offset:34816
	ds_read_b128 v[200:203], v159 offset:35840
	ds_read_b128 v[204:207], v159 offset:36864
	ds_read_b128 v[208:211], v159 offset:37888
	ds_read_b128 v[234:237], v159 offset:38912
	ds_read_b128 v[244:247], v159 offset:39936
	global_load_lds_dwordx4 v[248:249], off
	v_lshl_add_u64 v[248:249], s[30:31], 0, v[130:131]
	s_mov_b32 m0, s38
	s_nop 0
	global_load_lds_dwordx4 v[248:249], off
	s_waitcnt vmcnt(8)
	s_waitcnt lgkmcnt(0)
	s_barrier
; #define PG8_STAGE(bufoff, gbase, voff) do { _Pragma("unroll") for (int _i = 0; _i < 2; ++_i) \
;         __builtin_amdgcn_global_load_lds((const unsigned*)((const char*)(gbase) + (voff)[_i]), (PG8_LAS unsigned*)(lds + (bufoff) + ldsw + _i * 8192), 16, 0, 0); } while (0)
; #define PG8_LDA(dst, b, h) do { _Pragma("unroll") for (int m = 0; m < 4; ++m) _Pragma("unroll") for (int k = 0; k < 2; ++k) dst[m][k] = *(const PG8_LAS bf16x8*)(lds + PG8_SA(b, h) + aoff + m * 2048 + k * 1024); } while (0)
; #define PG8_MMA(ai, bj, At, Bt) do { __builtin_amdgcn_s_setprio(1); _Pragma("unroll") for (int m = 0; m < 4; ++m) _Pragma("unroll") for (int n = 0; n < 2; ++n) _Pragma("unroll") for (int k = 0; k < 2; ++k) \
;         acc[ai][bj][m][n] = __builtin_amdgcn_mfma_f32_16x16x32_bf16(Bt[n][k], At[m][k], acc[ai][bj][m][n], 0, 0, 0); __builtin_amdgcn_s_setprio(0); } while (0)
; #define PG8_WAIT_V(n) asm volatile("s_waitcnt vmcnt(" #n ")" ::: "memory")
; #define PG8_WAIT_L(n) asm volatile("s_waitcnt lgkmcnt(" #n ")" ::: "memory")
; #define PG8_BAR __builtin_amdgcn_s_barrier()
; #define PG8_SCHED __builtin_amdgcn_sched_barrier(0)
; template <class Epi, class Sched, bool ALIGN_EPI = false, bool SP2 = false>
; __device__ __forceinline__ void gemm_phase(PG8_LAS unsigned char* lds, const Gemm g, const Sched& S, const Epi& E) {
;     ...
;         for (int t = 0; t < nt; t += 2) {
;             const bool last = (t == nt - 2);
;             const char* a1 = cA + (size_t)(t + 1) * kstep;
;             const char* a2 = last ? nA : cA + (size_t)(t + 2) * kstep; const char* b2 = last ? nB : cB + (size_t)(t + 2) * kstep;
;             const char* a3 = a2 + kstep; const char* b3 = b2 + kstep;
;     ...
;             PG8_WAIT_V(8); PG8_WAIT_L(0); PG8_BAR; PG8_MMA(0, 0, At, B0); PG8_MMA(0, 1, At, B1); PG8_BAR; PG8_SCHED;
;             PG8_LDA(At, 1, 1); PG8_STAGE(PG8_SB(1, 0), b3, voffB); PG8_STAGE(PG8_SB(1, 1), b3 + hstep, voffB); PG8_STAGE(PG8_SA(1, 0), a3, voffA);
;             PG8_WAIT_V(8); PG8_WAIT_L(0); PG8_BAR; PG8_MMA(1, 0, At, B0); PG8_MMA(1, 1, At, B1); PG8_BAR; PG8_SCHED;
	s_setprio 1
	s_waitcnt lgkmcnt(0)
	v_mfma_f32_16x16x32_bf16 v[124:127], v[138:141], v[188:191], v[124:127]
	v_mfma_f32_16x16x32_bf16 v[120:123], v[164:167], v[188:191], v[120:123]
	v_mfma_f32_16x16x32_bf16 v[108:111], v[138:141], v[196:199], v[108:111]
	v_mfma_f32_16x16x32_bf16 v[104:107], v[164:167], v[196:199], v[104:107]
	v_mfma_f32_16x16x32_bf16 v[92:95], v[138:141], v[204:207], v[92:95]
	v_mfma_f32_16x16x32_bf16 v[88:91], v[164:167], v[204:207], v[88:91]
	v_mfma_f32_16x16x32_bf16 v[76:79], v[138:141], v[234:237], v[76:79]
	v_mfma_f32_16x16x32_bf16 v[72:75], v[164:167], v[234:237], v[72:75]
	v_mfma_f32_16x16x32_bf16 v[124:127], v[160:163], v[192:195], v[124:127]
	v_mfma_f32_16x16x32_bf16 v[120:123], v[168:171], v[192:195], v[120:123]
	v_mfma_f32_16x16x32_bf16 v[108:111], v[160:163], v[200:203], v[108:111]
	v_mfma_f32_16x16x32_bf16 v[104:107], v[168:171], v[200:203], v[104:107]
	v_mfma_f32_16x16x32_bf16 v[92:95], v[160:163], v[208:211], v[92:95]
	v_mfma_f32_16x16x32_bf16 v[88:91], v[168:171], v[208:211], v[88:91]
	v_mfma_f32_16x16x32_bf16 v[76:79], v[160:163], v[244:247], v[76:79]
	v_mfma_f32_16x16x32_bf16 v[72:75], v[168:171], v[244:247], v[72:75]
	s_setprio 0
	s_setprio 1
	v_mfma_f32_16x16x32_bf16 v[116:119], v[172:175], v[188:191], v[116:119]
	v_mfma_f32_16x16x32_bf16 v[112:115], v[180:183], v[188:191], v[112:115]
	v_mfma_f32_16x16x32_bf16 v[100:103], v[172:175], v[196:199], v[100:103]
	v_mfma_f32_16x16x32_bf16 v[96:99], v[180:183], v[196:199], v[96:99]
	v_mfma_f32_16x16x32_bf16 v[84:87], v[172:175], v[204:207], v[84:87]
	v_mfma_f32_16x16x32_bf16 v[80:83], v[180:183], v[204:207], v[80:83]
	v_mfma_f32_16x16x32_bf16 v[68:71], v[172:175], v[234:237], v[68:71]
	v_mfma_f32_16x16x32_bf16 v[64:67], v[180:183], v[234:237], v[64:67]
	v_mfma_f32_16x16x32_bf16 v[116:119], v[176:179], v[192:195], v[116:119]
	v_mfma_f32_16x16x32_bf16 v[112:115], v[184:187], v[192:195], v[112:115]
	v_mfma_f32_16x16x32_bf16 v[100:103], v[176:179], v[200:203], v[100:103]
	v_mfma_f32_16x16x32_bf16 v[96:99], v[184:187], v[200:203], v[96:99]
	v_mfma_f32_16x16x32_bf16 v[84:87], v[176:179], v[208:211], v[84:87]
	v_mfma_f32_16x16x32_bf16 v[80:83], v[184:187], v[208:211], v[80:83]
	v_mfma_f32_16x16x32_bf16 v[68:71], v[176:179], v[244:247], v[68:71]
	v_mfma_f32_16x16x32_bf16 v[64:67], v[184:187], v[244:247], v[64:67]
	s_setprio 0
	s_barrier
	s_add_i32 s30, s50, s0
	v_lshl_add_u64 v[142:143], v[142:143], 0, s[54:55]
	s_mov_b32 m0, s30
	ds_read_b128 v[188:191], v159 offset:49152
	ds_read_b128 v[192:195], v159 offset:50176
	ds_read_b128 v[196:199], v159 offset:51200
	ds_read_b128 v[200:203], v159 offset:52224
	ds_read_b128 v[204:207], v159 offset:53248
	ds_read_b128 v[208:211], v159 offset:54272
	ds_read_b128 v[234:237], v159 offset:55296
	ds_read_b128 v[244:247], v159 offset:56320
	global_load_lds_dwordx4 v[142:143], off
	s_add_i32 m0, s30, 0x2000
	s_add_u32 s28, s28, 0x40080
	v_lshl_add_u64 v[142:143], v[154:155], 0, s[54:55]
	s_addc_u32 s29, s29, 0
	s_add_i32 s30, s51, s0
	global_load_lds_dwordx4 v[142:143], off
	v_lshl_add_u64 v[142:143], s[28:29], 0, v[144:145]
	s_mov_b32 m0, s30
	s_nop 0
	global_load_lds_dwordx4 v[142:143], off
	v_lshl_add_u64 v[142:143], s[28:29], 0, v[132:133]
	s_add_i32 m0, s30, 0x2000
	s_nop 0
	global_load_lds_dwordx4 v[142:143], off
	v_lshl_add_u64 v[142:143], v[214:215], 0, s[54:55]
	s_mov_b32 m0, s39
	s_nop 0
	global_load_lds_dwordx4 v[142:143], off
	v_lshl_add_u64 v[142:143], v[238:239], 0, s[54:55]
	s_mov_b32 m0, s40
	s_nop 0
	global_load_lds_dwordx4 v[142:143], off
	s_waitcnt vmcnt(8)
	s_waitcnt lgkmcnt(0)
	s_barrier
	s_setprio 1
	s_waitcnt lgkmcnt(0)
	v_mfma_f32_16x16x32_bf16 v[60:63], v[138:141], v[188:191], v[60:63]
	v_mfma_f32_16x16x32_bf16 v[56:59], v[164:167], v[188:191], v[56:59]
	v_mfma_f32_16x16x32_bf16 v[44:47], v[138:141], v[196:199], v[44:47]
	v_mfma_f32_16x16x32_bf16 v[40:43], v[164:167], v[196:199], v[40:43]
	v_mfma_f32_16x16x32_bf16 v[28:31], v[138:141], v[204:207], v[28:31]
	v_mfma_f32_16x16x32_bf16 v[24:27], v[164:167], v[204:207], v[24:27]
	v_mfma_f32_16x16x32_bf16 v[12:15], v[138:141], v[234:237], v[12:15]
	v_mfma_f32_16x16x32_bf16 v[8:11], v[164:167], v[234:237], v[8:11]
	v_mfma_f32_16x16x32_bf16 v[60:63], v[160:163], v[192:195], v[60:63]
	v_mfma_f32_16x16x32_bf16 v[56:59], v[168:171], v[192:195], v[56:59]
	v_mfma_f32_16x16x32_bf16 v[44:47], v[160:163], v[200:203], v[44:47]
	v_mfma_f32_16x16x32_bf16 v[40:43], v[168:171], v[200:203], v[40:43]
	v_mfma_f32_16x16x32_bf16 v[28:31], v[160:163], v[208:211], v[28:31]
	v_mfma_f32_16x16x32_bf16 v[24:27], v[168:171], v[208:211], v[24:27]
	v_mfma_f32_16x16x32_bf16 v[12:15], v[160:163], v[244:247], v[12:15]
	v_mfma_f32_16x16x32_bf16 v[8:11], v[168:171], v[244:247], v[8:11]
	s_setprio 0
	s_setprio 1
	v_mfma_f32_16x16x32_bf16 v[52:55], v[172:175], v[188:191], v[52:55]
	v_mfma_f32_16x16x32_bf16 v[48:51], v[180:183], v[188:191], v[48:51]
	v_mfma_f32_16x16x32_bf16 v[36:39], v[172:175], v[196:199], v[36:39]
	v_mfma_f32_16x16x32_bf16 v[32:35], v[180:183], v[196:199], v[32:35]
	v_mfma_f32_16x16x32_bf16 v[20:23], v[172:175], v[204:207], v[20:23]
	v_mfma_f32_16x16x32_bf16 v[16:19], v[180:183], v[204:207], v[16:19]
	v_mfma_f32_16x16x32_bf16 v[4:7], v[172:175], v[234:237], v[4:7]
	v_mfma_f32_16x16x32_bf16 v[0:3], v[180:183], v[234:237], v[0:3]
	v_mfma_f32_16x16x32_bf16 v[52:55], v[176:179], v[192:195], v[52:55]
	v_mfma_f32_16x16x32_bf16 v[48:51], v[184:187], v[192:195], v[48:51]
	v_mfma_f32_16x16x32_bf16 v[36:39], v[176:179], v[200:203], v[36:39]
	v_mfma_f32_16x16x32_bf16 v[32:35], v[184:187], v[200:203], v[32:35]
	v_mfma_f32_16x16x32_bf16 v[20:23], v[176:179], v[208:211], v[20:23]
	v_mfma_f32_16x16x32_bf16 v[16:19], v[184:187], v[208:211], v[16:19]
	v_mfma_f32_16x16x32_bf16 v[4:7], v[176:179], v[244:247], v[4:7]
	v_mfma_f32_16x16x32_bf16 v[0:3], v[184:187], v[244:247], v[0:3]
	s_setprio 0
	s_add_i32 s49, s49, 2
	s_add_u32 s43, s43, 0x100
	s_addc_u32 s48, s48, 0
	s_add_u32 s26, s26, 0x100
	s_addc_u32 s27, s27, 0
	s_add_u32 s28, s26, 0xfffc0080
	s_addc_u32 s29, s27, -1
	s_add_i32 s50, 0, 0x10000
	s_cmp_eq_u32 s49, 12
	s_cselect_b32 s31, s17, s29
	s_cselect_b32 s30, s23, s28
	v_add_u32_e32 v142, s50, v157
	s_cselect_b32 s29, s15, s48
	s_cselect_b32 s28, s42, s43
	s_add_i32 s52, 0, 0x14000
	s_barrier
	s_cmp_gt_u32 s49, 13
	s_cbranch_scc0 .LBB0_1205
	s_and_b64 vcc, exec, s[6:7]
	s_cbranch_vccz .LBB0_1208
	s_barrier

; #define PG8_STAGE(bufoff, gbase, voff) do { _Pragma("unroll") for (int _i = 0; _i < 2; ++_i) \
;         __builtin_amdgcn_global_load_lds((const unsigned*)((const char*)(gbase) + (voff)[_i]), (PG8_LAS unsigned*)(lds + (bufoff) + ldsw + _i * 8192), 16, 0, 0); } while (0)
; #define PG8_LDA(dst, b, h) do { _Pragma("unroll") for (int m = 0; m < 4; ++m) _Pragma("unroll") for (int k = 0; k < 2; ++k) dst[m][k] = *(const PG8_LAS bf16x8*)(lds + PG8_SA(b, h) + aoff + m * 2048 + k * 1024); } while (0)
; #define PG8_LDB(dst, b, h) do { _Pragma("unroll") for (int n = 0; n < 2; ++n) _Pragma("unroll") for (int k = 0; k < 2; ++k) dst[n][k] = *(const PG8_LAS bf16x8*)(lds + PG8_SB(b, h) + boff + n * 2048 + k * 1024); } while (0)
; #define PG8_WAIT_V(n) asm volatile("s_waitcnt vmcnt(" #n ")" ::: "memory")
; #define PG8_BAR __builtin_amdgcn_s_barrier()
; template <class Epi, class Sched, bool ALIGN_EPI = false, bool SP2 = false>
; __device__ __forceinline__ void gemm_phase(PG8_LAS unsigned char* lds, const Gemm g, const Sched& S, const Epi& E) {
;     ...
;         const bool has_next = S.next(ui + 1, nxt);
;         const char* nA = has_next ? (const char*)g.A + (size_t)nxt.pm * tstep + (size_t)nxt.kt0 * kstep : cA; const char* nB = has_next ? (const char*)g.Bt + (size_t)nxt.pn * tstep + (size_t)nxt.kt0 * kstep : cB;
;         const int nt = cur.nkt;
;         for (int t = 0; t < nt; t += 2) {
;             const bool last = (t == nt - 2);
;             const char* a1 = cA + (size_t)(t + 1) * kstep;
;             const char* a2 = last ? nA : cA + (size_t)(t + 2) * kstep; const char* b2 = last ? nB : cB + (size_t)(t + 2) * kstep;
;             const char* a3 = a2 + kstep; const char* b3 = b2 + kstep;
;             if (last && has_next) S.a_ready(nxt);
;             if constexpr (SP2) {
;             PG8_LDB(B0, 0, 0); PG8_LDB(B1, 0, 1); PG8_SCHED; PG8_LDA(At, 0, 0); PG8_STAGE(PG8_SA(1, 1), a1 + hstep, voffA);
;             PG8_WAIT_V(8); PG8_WAIT_L(0); PG8_BAR; PG8_MMA(0, 0, At, B0); PG8_MMA(0, 1, At, B1); PG8_BAR; PG8_SCHED;
;     ...
; #pragma unroll
;         for (int a = 0; a < 2; ++a)
; #pragma unroll
;             for (int b = 0; b < 2; ++b)
; #pragma unroll
;                 for (int m = 0; m < 4; ++m)
; #pragma unroll
;                     for (int n = 0; n < 2; ++n) acc[a][b][m][n] = (f32x4){0.f, 0.f, 0.f, 0.f};
;         cur = nxt; cA = nA; cB = nB; ++ui;
.LBB0_1294:
	s_ashr_i32 s17, s16, 31
	s_lshl_b64 s[18:19], s[16:17], 19
	s_add_u32 s18, s0, s18
	s_addc_u32 s19, s28, s19
	s_and_b64 s[20:21], s[6:7], exec
	s_cselect_b32 s17, s19, s25
	s_cselect_b32 s42, s18, s24
	s_ashr_i32 s15, s14, 31
	s_lshl_b64 s[20:21], s[14:15], 19
	s_add_u32 s20, s29, s20
	s_addc_u32 s21, s30, s21
	s_and_b64 s[26:27], s[6:7], exec
	s_cselect_b32 s15, s21, s23
	s_cselect_b32 s43, s20, s22
	s_add_u32 s44, s22, 0x100
	s_addc_u32 s45, s23, 0
	s_add_u32 s22, s24, 0x40080
	v_mov_b32_e32 v0, 0
	s_addc_u32 s23, s25, 0
	s_mov_b32 s46, -2
	v_mov_b64_e32 v[0:1], 0
	v_mov_b64_e32 v[2:3], 0
	v_mov_b64_e32 v[8:9], 0
	v_mov_b64_e32 v[10:11], 0
	v_mov_b64_e32 v[16:17], 0
	v_mov_b64_e32 v[18:19], 0
	v_mov_b64_e32 v[24:25], 0
	v_mov_b64_e32 v[26:27], 0
	v_mov_b64_e32 v[32:33], 0
	v_mov_b64_e32 v[34:35], 0
	v_mov_b64_e32 v[40:41], 0
	v_mov_b64_e32 v[42:43], 0
	v_mov_b64_e32 v[48:49], 0
	v_mov_b64_e32 v[50:51], 0
	v_mov_b64_e32 v[56:57], 0
	v_mov_b64_e32 v[58:59], 0
	v_mov_b64_e32 v[4:5], 0
	v_mov_b64_e32 v[6:7], 0
	v_mov_b64_e32 v[12:13], 0
	v_mov_b64_e32 v[14:15], 0
	v_mov_b64_e32 v[20:21], 0
	v_mov_b64_e32 v[22:23], 0
	v_mov_b64_e32 v[28:29], 0
	v_mov_b64_e32 v[30:31], 0
	v_mov_b64_e32 v[36:37], 0
	v_mov_b64_e32 v[38:39], 0
	v_mov_b64_e32 v[44:45], 0
	v_mov_b64_e32 v[46:47], 0
	v_mov_b64_e32 v[52:53], 0
	v_mov_b64_e32 v[54:55], 0
	v_mov_b64_e32 v[60:61], 0
	v_mov_b64_e32 v[62:63], 0
	v_mov_b64_e32 v[64:65], 0
	v_mov_b64_e32 v[66:67], 0
	v_mov_b64_e32 v[72:73], 0
	v_mov_b64_e32 v[74:75], 0
	v_mov_b64_e32 v[80:81], 0
	v_mov_b64_e32 v[82:83], 0
	v_mov_b64_e32 v[88:89], 0
	v_mov_b64_e32 v[90:91], 0
	v_mov_b64_e32 v[96:97], 0
	v_mov_b64_e32 v[98:99], 0
	v_mov_b64_e32 v[104:105], 0
	v_mov_b64_e32 v[106:107], 0
	v_mov_b64_e32 v[112:113], 0
	v_mov_b64_e32 v[114:115], 0
	v_mov_b64_e32 v[120:121], 0
	v_mov_b64_e32 v[122:123], 0
	v_mov_b64_e32 v[68:69], 0
	v_mov_b64_e32 v[70:71], 0
	v_mov_b64_e32 v[76:77], 0
	v_mov_b64_e32 v[78:79], 0
	v_mov_b64_e32 v[84:85], 0
	v_mov_b64_e32 v[86:87], 0
	v_mov_b64_e32 v[92:93], 0
	v_mov_b64_e32 v[94:95], 0
	v_mov_b64_e32 v[100:101], 0
	v_mov_b64_e32 v[102:103], 0
	v_mov_b64_e32 v[108:109], 0
	v_mov_b64_e32 v[110:111], 0
	v_mov_b64_e32 v[116:117], 0
	v_mov_b64_e32 v[118:119], 0
	v_mov_b64_e32 v[124:125], 0
	v_mov_b64_e32 v[126:127], 0
	s_mov_b64 s[52:53], 0x80
	s_add_u32 s24, s22, 0xfffc0080
	s_addc_u32 s25, s23, -1
	s_add_i32 s47, 0, 0x10000
	s_cmp_eq_u32 s46, 12
	s_cselect_b32 s27, s17, s25
	s_cselect_b32 s26, s42, s24
	v_add_u32_e32 v142, s47, v156
	s_cselect_b32 s25, s15, s45
	s_cselect_b32 s24, s43, s44
	s_add_i32 s50, 0, 0x14000
.LBB0_1295:
	ds_read_b128 v[138:141], v142
	ds_read_b128 v[160:163], v142 offset:1024
	ds_read_b128 v[164:167], v142 offset:2048
	ds_read_b128 v[168:171], v142 offset:3072
	v_add_u32_e32 v142, s50, v156
	ds_read_b128 v[172:175], v142
	ds_read_b128 v[176:179], v142 offset:1024
	ds_read_b128 v[180:183], v142 offset:2048
	ds_read_b128 v[184:187], v142 offset:3072
	v_lshl_add_u64 v[142:143], s[22:23], 0, v[136:137]
	s_add_i32 m0, s34, 0xc000
	ds_read_b128 v[188:191], v158
	ds_read_b128 v[192:195], v158 offset:1024
	ds_read_b128 v[196:199], v158 offset:2048
	ds_read_b128 v[200:203], v158 offset:3072
	ds_read_b128 v[204:207], v158 offset:4096
	ds_read_b128 v[208:211], v158 offset:5120
	ds_read_b128 v[234:237], v158 offset:6144
	ds_read_b128 v[244:247], v158 offset:7168
	global_load_lds_dwordx4 v[142:143], off
	v_lshl_add_u64 v[142:143], s[22:23], 0, v[134:135]
	s_add_i32 m0, s34, 0xe000
	s_nop 0
	global_load_lds_dwordx4 v[142:143], off
	s_waitcnt vmcnt(8)
	s_waitcnt lgkmcnt(0)
	s_barrier
	s_setprio 1
	s_waitcnt lgkmcnt(0)
	v_mfma_f32_16x16x32_bf16 v[124:127], v[138:141], v[188:191], v[124:127]
	v_mfma_f32_16x16x32_bf16 v[116:119], v[164:167], v[188:191], v[116:119]
	v_mfma_f32_16x16x32_bf16 v[108:111], v[138:141], v[196:199], v[108:111]
	v_mfma_f32_16x16x32_bf16 v[100:103], v[164:167], v[196:199], v[100:103]
	v_mfma_f32_16x16x32_bf16 v[92:95], v[138:141], v[204:207], v[92:95]
	v_mfma_f32_16x16x32_bf16 v[84:87], v[164:167], v[204:207], v[84:87]
	v_mfma_f32_16x16x32_bf16 v[76:79], v[138:141], v[234:237], v[76:79]
	v_mfma_f32_16x16x32_bf16 v[68:71], v[164:167], v[234:237], v[68:71]
	v_mfma_f32_16x16x32_bf16 v[124:127], v[160:163], v[192:195], v[124:127]
	v_mfma_f32_16x16x32_bf16 v[116:119], v[168:171], v[192:195], v[116:119]
	v_mfma_f32_16x16x32_bf16 v[108:111], v[160:163], v[200:203], v[108:111]
	v_mfma_f32_16x16x32_bf16 v[100:103], v[168:171], v[200:203], v[100:103]
	v_mfma_f32_16x16x32_bf16 v[92:95], v[160:163], v[208:211], v[92:95]
	v_mfma_f32_16x16x32_bf16 v[84:87], v[168:171], v[208:211], v[84:87]
	v_mfma_f32_16x16x32_bf16 v[76:79], v[160:163], v[244:247], v[76:79]
	v_mfma_f32_16x16x32_bf16 v[68:71], v[168:171], v[244:247], v[68:71]
	s_setprio 0
	s_setprio 1
	v_mfma_f32_16x16x32_bf16 v[120:123], v[172:175], v[188:191], v[120:123]
	v_mfma_f32_16x16x32_bf16 v[112:115], v[180:183], v[188:191], v[112:115]
	v_mfma_f32_16x16x32_bf16 v[104:107], v[172:175], v[196:199], v[104:107]
	v_mfma_f32_16x16x32_bf16 v[96:99], v[180:183], v[196:199], v[96:99]
	v_mfma_f32_16x16x32_bf16 v[88:91], v[172:175], v[204:207], v[88:91]
	v_mfma_f32_16x16x32_bf16 v[80:83], v[180:183], v[204:207], v[80:83]
	v_mfma_f32_16x16x32_bf16 v[72:75], v[172:175], v[234:237], v[72:75]
	v_mfma_f32_16x16x32_bf16 v[64:67], v[180:183], v[234:237], v[64:67]
	v_mfma_f32_16x16x32_bf16 v[120:123], v[176:179], v[192:195], v[120:123]
	v_mfma_f32_16x16x32_bf16 v[112:115], v[184:187], v[192:195], v[112:115]
	v_mfma_f32_16x16x32_bf16 v[104:107], v[176:179], v[200:203], v[104:107]
	v_mfma_f32_16x16x32_bf16 v[96:99], v[184:187], v[200:203], v[96:99]
	v_mfma_f32_16x16x32_bf16 v[88:91], v[176:179], v[208:211], v[88:91]
	v_mfma_f32_16x16x32_bf16 v[80:83], v[184:187], v[208:211], v[80:83]
	v_mfma_f32_16x16x32_bf16 v[72:75], v[176:179], v[244:247], v[72:75]
	v_mfma_f32_16x16x32_bf16 v[64:67], v[184:187], v[244:247], v[64:67]
	s_setprio 0
	s_barrier
; #define PG8_STAGE(bufoff, gbase, voff) do { _Pragma("unroll") for (int _i = 0; _i < 2; ++_i) \
;         __builtin_amdgcn_global_load_lds((const unsigned*)((const char*)(gbase) + (voff)[_i]), (PG8_LAS unsigned*)(lds + (bufoff) + ldsw + _i * 8192), 16, 0, 0); } while (0)
; #define PG8_LDA(dst, b, h) do { _Pragma("unroll") for (int m = 0; m < 4; ++m) _Pragma("unroll") for (int k = 0; k < 2; ++k) dst[m][k] = *(const PG8_LAS bf16x8*)(lds + PG8_SA(b, h) + aoff + m * 2048 + k * 1024); } while (0)
; #define PG8_LDB(dst, b, h) do { _Pragma("unroll") for (int n = 0; n < 2; ++n) _Pragma("unroll") for (int k = 0; k < 2; ++k) dst[n][k] = *(const PG8_LAS bf16x8*)(lds + PG8_SB(b, h) + boff + n * 2048 + k * 1024); } while (0)
; #define PG8_MMA(ai, bj, At, Bt) do { __builtin_amdgcn_s_setprio(1); _Pragma("unroll") for (int m = 0; m < 4; ++m) _Pragma("unroll") for (int n = 0; n < 2; ++n) _Pragma("unroll") for (int k = 0; k < 2; ++k) \
;         acc[ai][bj][m][n] = __builtin_amdgcn_mfma_f32_16x16x32_bf16(Bt[n][k], At[m][k], acc[ai][bj][m][n], 0, 0, 0); __builtin_amdgcn_s_setprio(0); } while (0)
; #define PG8_WAIT_V(n) asm volatile("s_waitcnt vmcnt(" #n ")" ::: "memory")
; #define PG8_WAIT_L(n) asm volatile("s_waitcnt lgkmcnt(" #n ")" ::: "memory")
; #define PG8_BAR __builtin_amdgcn_s_barrier()
; #define PG8_SCHED __builtin_amdgcn_sched_barrier(0)
; template <class Epi, class Sched, bool ALIGN_EPI = false, bool SP2 = false>
; __device__ __forceinline__ void gemm_phase(PG8_LAS unsigned char* lds, const Gemm g, const Sched& S, const Epi& E) {
;     ...
;             PG8_LDB(B0, 0, 0); PG8_LDB(B1, 0, 1); PG8_SCHED; PG8_LDA(At, 0, 0); PG8_STAGE(PG8_SA(1, 1), a1 + hstep, voffA);
;             PG8_WAIT_V(8); PG8_WAIT_L(0); PG8_BAR; PG8_MMA(0, 0, At, B0); PG8_MMA(0, 1, At, B1); PG8_BAR; PG8_SCHED;
;             PG8_LDA(At, 0, 1); PG8_STAGE(PG8_SB(0, 0), b2, voffB); PG8_STAGE(PG8_SB(0, 1), b2 + hstep, voffB); PG8_STAGE(PG8_SA(0, 0), a2, voffA);
;             PG8_WAIT_V(8); PG8_WAIT_L(0); PG8_BAR; PG8_MMA(1, 0, At, B0); PG8_MMA(1, 1, At, B1); PG8_BAR; PG8_SCHED;
;             PG8_LDB(B0, 1, 0); PG8_LDB(B1, 1, 1); PG8_SCHED; PG8_LDA(At, 1, 0); PG8_STAGE(PG8_SA(0, 1), a2 + hstep, voffA);
;             PG8_WAIT_V(8); PG8_WAIT_L(0); PG8_BAR; PG8_MMA(0, 0, At, B0); PG8_MMA(0, 1, At, B1); PG8_BAR; PG8_SCHED;
	s_add_i32 s47, s47, s31
	v_lshl_add_u64 v[142:143], s[24:25], 0, v[144:145]
	s_mov_b32 m0, s47
	ds_read_b128 v[188:191], v158 offset:16384
	ds_read_b128 v[192:195], v158 offset:17408
	ds_read_b128 v[196:199], v158 offset:18432
	ds_read_b128 v[200:203], v158 offset:19456
	ds_read_b128 v[204:207], v158 offset:20480
	ds_read_b128 v[208:211], v158 offset:21504
	ds_read_b128 v[234:237], v158 offset:22528
	ds_read_b128 v[244:247], v158 offset:23552
	global_load_lds_dwordx4 v[142:143], off
	s_add_i32 m0, s47, 0x2000
	s_add_u32 s48, s24, 0x40000
	v_lshl_add_u64 v[214:215], s[24:25], 0, v[128:129]
	s_addc_u32 s49, s25, 0
	s_add_i32 s47, s50, s31
	global_load_lds_dwordx4 v[214:215], off
	v_lshl_add_u64 v[238:239], s[48:49], 0, v[144:145]
	s_mov_b32 m0, s47
	v_lshl_add_u64 v[248:249], s[26:27], 0, v[130:131]
	global_load_lds_dwordx4 v[238:239], off
	v_lshl_add_u64 v[238:239], s[48:49], 0, v[128:129]
	s_add_i32 m0, s47, 0x2000
	s_nop 0
	global_load_lds_dwordx4 v[238:239], off
	v_lshl_add_u64 v[238:239], s[26:27], 0, v[132:133]
	s_mov_b32 m0, s34
	s_nop 0
	global_load_lds_dwordx4 v[238:239], off
	s_mov_b32 m0, s35
	s_nop 0
	global_load_lds_dwordx4 v[248:249], off
	s_waitcnt vmcnt(8)
	s_waitcnt lgkmcnt(0)
	s_barrier
	s_setprio 1
	s_waitcnt lgkmcnt(0)
	v_mfma_f32_16x16x32_bf16 v[60:63], v[138:141], v[188:191], v[60:63]
	v_mfma_f32_16x16x32_bf16 v[52:55], v[164:167], v[188:191], v[52:55]
	v_mfma_f32_16x16x32_bf16 v[44:47], v[138:141], v[196:199], v[44:47]
	v_mfma_f32_16x16x32_bf16 v[36:39], v[164:167], v[196:199], v[36:39]
	v_mfma_f32_16x16x32_bf16 v[28:31], v[138:141], v[204:207], v[28:31]
	v_mfma_f32_16x16x32_bf16 v[20:23], v[164:167], v[204:207], v[20:23]
	v_mfma_f32_16x16x32_bf16 v[12:15], v[138:141], v[234:237], v[12:15]
	v_mfma_f32_16x16x32_bf16 v[4:7], v[164:167], v[234:237], v[4:7]
	v_mfma_f32_16x16x32_bf16 v[60:63], v[160:163], v[192:195], v[60:63]
	v_mfma_f32_16x16x32_bf16 v[52:55], v[168:171], v[192:195], v[52:55]
	v_mfma_f32_16x16x32_bf16 v[44:47], v[160:163], v[200:203], v[44:47]
	v_mfma_f32_16x16x32_bf16 v[36:39], v[168:171], v[200:203], v[36:39]
	v_mfma_f32_16x16x32_bf16 v[28:31], v[160:163], v[208:211], v[28:31]
	v_mfma_f32_16x16x32_bf16 v[20:23], v[168:171], v[208:211], v[20:23]
	v_mfma_f32_16x16x32_bf16 v[12:15], v[160:163], v[244:247], v[12:15]
	v_mfma_f32_16x16x32_bf16 v[4:7], v[168:171], v[244:247], v[4:7]
	s_setprio 0
	s_setprio 1
	v_mfma_f32_16x16x32_bf16 v[56:59], v[172:175], v[188:191], v[56:59]
	v_mfma_f32_16x16x32_bf16 v[48:51], v[180:183], v[188:191], v[48:51]
	v_mfma_f32_16x16x32_bf16 v[40:43], v[172:175], v[196:199], v[40:43]
	v_mfma_f32_16x16x32_bf16 v[32:35], v[180:183], v[196:199], v[32:35]
	v_mfma_f32_16x16x32_bf16 v[24:27], v[172:175], v[204:207], v[24:27]
	v_mfma_f32_16x16x32_bf16 v[16:19], v[180:183], v[204:207], v[16:19]
	v_mfma_f32_16x16x32_bf16 v[8:11], v[172:175], v[234:237], v[8:11]
	v_mfma_f32_16x16x32_bf16 v[0:3], v[180:183], v[234:237], v[0:3]
	v_mfma_f32_16x16x32_bf16 v[56:59], v[176:179], v[192:195], v[56:59]
	v_mfma_f32_16x16x32_bf16 v[48:51], v[184:187], v[192:195], v[48:51]
	v_mfma_f32_16x16x32_bf16 v[40:43], v[176:179], v[200:203], v[40:43]
	v_mfma_f32_16x16x32_bf16 v[32:35], v[184:187], v[200:203], v[32:35]
	v_mfma_f32_16x16x32_bf16 v[24:27], v[176:179], v[208:211], v[24:27]
	v_mfma_f32_16x16x32_bf16 v[16:19], v[184:187], v[208:211], v[16:19]
	v_mfma_f32_16x16x32_bf16 v[8:11], v[176:179], v[244:247], v[8:11]
	v_mfma_f32_16x16x32_bf16 v[0:3], v[184:187], v[244:247], v[0:3]
	s_setprio 0
	s_barrier
	s_add_i32 s47, 0, 0x18000
	v_add_u32_e32 v154, s47, v156
	s_add_i32 s48, 0, 0x1c000
	ds_read_b128 v[138:141], v154
	ds_read_b128 v[160:163], v154 offset:1024
	ds_read_b128 v[164:167], v154 offset:2048
	ds_read_b128 v[168:171], v154 offset:3072
	v_add_u32_e32 v154, s48, v156
	ds_read_b128 v[172:175], v154
	ds_read_b128 v[176:179], v154 offset:1024
	ds_read_b128 v[180:183], v154 offset:2048
	ds_read_b128 v[184:187], v154 offset:3072
	s_add_u32 s26, s26, 0x40000
	s_addc_u32 s27, s27, 0
	s_mov_b32 m0, s36
	v_lshl_add_u64 v[250:251], s[26:27], 0, v[132:133]
	ds_read_b128 v[188:191], v158 offset:32768
	ds_read_b128 v[192:195], v158 offset:33792
	ds_read_b128 v[196:199], v158 offset:34816
	ds_read_b128 v[200:203], v158 offset:35840
	ds_read_b128 v[204:207], v158 offset:36864
	ds_read_b128 v[208:211], v158 offset:37888
	ds_read_b128 v[234:237], v158 offset:38912
	ds_read_b128 v[244:247], v158 offset:39936
	global_load_lds_dwordx4 v[250:251], off
	v_lshl_add_u64 v[250:251], s[26:27], 0, v[130:131]
	s_mov_b32 m0, s37
	s_nop 0
	global_load_lds_dwordx4 v[250:251], off
	s_waitcnt vmcnt(8)
	s_waitcnt lgkmcnt(0)
	s_barrier
; #define PG8_STAGE(bufoff, gbase, voff) do { _Pragma("unroll") for (int _i = 0; _i < 2; ++_i) \
;         __builtin_amdgcn_global_load_lds((const unsigned*)((const char*)(gbase) + (voff)[_i]), (PG8_LAS unsigned*)(lds + (bufoff) + ldsw + _i * 8192), 16, 0, 0); } while (0)
; #define PG8_LDA(dst, b, h) do { _Pragma("unroll") for (int m = 0; m < 4; ++m) _Pragma("unroll") for (int k = 0; k < 2; ++k) dst[m][k] = *(const PG8_LAS bf16x8*)(lds + PG8_SA(b, h) + aoff + m * 2048 + k * 1024); } while (0)
; #define PG8_MMA(ai, bj, At, Bt) do { __builtin_amdgcn_s_setprio(1); _Pragma("unroll") for (int m = 0; m < 4; ++m) _Pragma("unroll") for (int n = 0; n < 2; ++n) _Pragma("unroll") for (int k = 0; k < 2; ++k) \
;         acc[ai][bj][m][n] = __builtin_amdgcn_mfma_f32_16x16x32_bf16(Bt[n][k], At[m][k], acc[ai][bj][m][n], 0, 0, 0); __builtin_amdgcn_s_setprio(0); } while (0)
; #define PG8_WAIT_V(n) asm volatile("s_waitcnt vmcnt(" #n ")" ::: "memory")
; #define PG8_WAIT_L(n) asm volatile("s_waitcnt lgkmcnt(" #n ")" ::: "memory")
; #define PG8_BAR __builtin_amdgcn_s_barrier()
; #define PG8_SCHED __builtin_amdgcn_sched_barrier(0)
; template <class Epi, class Sched, bool ALIGN_EPI = false, bool SP2 = false>
; __device__ __forceinline__ void gemm_phase(PG8_LAS unsigned char* lds, const Gemm g, const Sched& S, const Epi& E) {
;     ...
;         for (int t = 0; t < nt; t += 2) {
;             const bool last = (t == nt - 2);
;             const char* a1 = cA + (size_t)(t + 1) * kstep;
;             const char* a2 = last ? nA : cA + (size_t)(t + 2) * kstep; const char* b2 = last ? nB : cB + (size_t)(t + 2) * kstep;
;             const char* a3 = a2 + kstep; const char* b3 = b2 + kstep;
;     ...
;             PG8_WAIT_V(8); PG8_WAIT_L(0); PG8_BAR; PG8_MMA(0, 0, At, B0); PG8_MMA(0, 1, At, B1); PG8_BAR; PG8_SCHED;
;             PG8_LDA(At, 1, 1); PG8_STAGE(PG8_SB(1, 0), b3, voffB); PG8_STAGE(PG8_SB(1, 1), b3 + hstep, voffB); PG8_STAGE(PG8_SA(1, 0), a3, voffA);
;             PG8_WAIT_V(8); PG8_WAIT_L(0); PG8_BAR; PG8_MMA(1, 0, At, B0); PG8_MMA(1, 1, At, B1); PG8_BAR; PG8_SCHED;
	s_setprio 1
	s_waitcnt lgkmcnt(0)
	v_mfma_f32_16x16x32_bf16 v[124:127], v[138:141], v[188:191], v[124:127]
	v_mfma_f32_16x16x32_bf16 v[116:119], v[164:167], v[188:191], v[116:119]
	v_mfma_f32_16x16x32_bf16 v[108:111], v[138:141], v[196:199], v[108:111]
	v_mfma_f32_16x16x32_bf16 v[100:103], v[164:167], v[196:199], v[100:103]
	v_mfma_f32_16x16x32_bf16 v[92:95], v[138:141], v[204:207], v[92:95]
	v_mfma_f32_16x16x32_bf16 v[84:87], v[164:167], v[204:207], v[84:87]
	v_mfma_f32_16x16x32_bf16 v[76:79], v[138:141], v[234:237], v[76:79]
	v_mfma_f32_16x16x32_bf16 v[68:71], v[164:167], v[234:237], v[68:71]
	v_mfma_f32_16x16x32_bf16 v[124:127], v[160:163], v[192:195], v[124:127]
	v_mfma_f32_16x16x32_bf16 v[116:119], v[168:171], v[192:195], v[116:119]
	v_mfma_f32_16x16x32_bf16 v[108:111], v[160:163], v[200:203], v[108:111]
	v_mfma_f32_16x16x32_bf16 v[100:103], v[168:171], v[200:203], v[100:103]
	v_mfma_f32_16x16x32_bf16 v[92:95], v[160:163], v[208:211], v[92:95]
	v_mfma_f32_16x16x32_bf16 v[84:87], v[168:171], v[208:211], v[84:87]
	v_mfma_f32_16x16x32_bf16 v[76:79], v[160:163], v[244:247], v[76:79]
	v_mfma_f32_16x16x32_bf16 v[68:71], v[168:171], v[244:247], v[68:71]
	s_setprio 0
	s_setprio 1
	v_mfma_f32_16x16x32_bf16 v[120:123], v[172:175], v[188:191], v[120:123]
	v_mfma_f32_16x16x32_bf16 v[112:115], v[180:183], v[188:191], v[112:115]
	v_mfma_f32_16x16x32_bf16 v[104:107], v[172:175], v[196:199], v[104:107]
	v_mfma_f32_16x16x32_bf16 v[96:99], v[180:183], v[196:199], v[96:99]
	v_mfma_f32_16x16x32_bf16 v[88:91], v[172:175], v[204:207], v[88:91]
	v_mfma_f32_16x16x32_bf16 v[80:83], v[180:183], v[204:207], v[80:83]
	v_mfma_f32_16x16x32_bf16 v[72:75], v[172:175], v[234:237], v[72:75]
	v_mfma_f32_16x16x32_bf16 v[64:67], v[180:183], v[234:237], v[64:67]
	v_mfma_f32_16x16x32_bf16 v[120:123], v[176:179], v[192:195], v[120:123]
	v_mfma_f32_16x16x32_bf16 v[112:115], v[184:187], v[192:195], v[112:115]
	v_mfma_f32_16x16x32_bf16 v[104:107], v[176:179], v[200:203], v[104:107]
	v_mfma_f32_16x16x32_bf16 v[96:99], v[184:187], v[200:203], v[96:99]
	v_mfma_f32_16x16x32_bf16 v[88:91], v[176:179], v[208:211], v[88:91]
	v_mfma_f32_16x16x32_bf16 v[80:83], v[184:187], v[208:211], v[80:83]
	v_mfma_f32_16x16x32_bf16 v[72:75], v[176:179], v[244:247], v[72:75]
	v_mfma_f32_16x16x32_bf16 v[64:67], v[184:187], v[244:247], v[64:67]
	s_setprio 0
	s_barrier
	s_add_i32 s26, s47, s31
	v_lshl_add_u64 v[142:143], v[142:143], 0, s[52:53]
	s_mov_b32 m0, s26
	ds_read_b128 v[188:191], v158 offset:49152
	ds_read_b128 v[192:195], v158 offset:50176
	ds_read_b128 v[196:199], v158 offset:51200
	ds_read_b128 v[200:203], v158 offset:52224
	ds_read_b128 v[204:207], v158 offset:53248
	ds_read_b128 v[208:211], v158 offset:54272
	ds_read_b128 v[234:237], v158 offset:55296
	ds_read_b128 v[244:247], v158 offset:56320
	global_load_lds_dwordx4 v[142:143], off
	s_add_i32 m0, s26, 0x2000
	s_add_u32 s24, s24, 0x40080
	v_lshl_add_u64 v[142:143], v[214:215], 0, s[52:53]
	s_addc_u32 s25, s25, 0
	s_add_i32 s26, s48, s31
	global_load_lds_dwordx4 v[142:143], off
	v_lshl_add_u64 v[142:143], s[24:25], 0, v[144:145]
	s_mov_b32 m0, s26
	s_nop 0
	global_load_lds_dwordx4 v[142:143], off
	v_lshl_add_u64 v[142:143], s[24:25], 0, v[128:129]
	s_add_i32 m0, s26, 0x2000
	s_nop 0
	global_load_lds_dwordx4 v[142:143], off
	v_lshl_add_u64 v[142:143], v[238:239], 0, s[52:53]
	s_mov_b32 m0, s33
	s_nop 0
	global_load_lds_dwordx4 v[142:143], off
	v_lshl_add_u64 v[142:143], v[248:249], 0, s[52:53]
	s_mov_b32 m0, s38
	s_nop 0
	global_load_lds_dwordx4 v[142:143], off
	s_waitcnt vmcnt(8)
	s_waitcnt lgkmcnt(0)
	s_barrier
	s_setprio 1
	s_waitcnt lgkmcnt(0)
	v_mfma_f32_16x16x32_bf16 v[60:63], v[138:141], v[188:191], v[60:63]
	v_mfma_f32_16x16x32_bf16 v[52:55], v[164:167], v[188:191], v[52:55]
	v_mfma_f32_16x16x32_bf16 v[44:47], v[138:141], v[196:199], v[44:47]
	v_mfma_f32_16x16x32_bf16 v[36:39], v[164:167], v[196:199], v[36:39]
	v_mfma_f32_16x16x32_bf16 v[28:31], v[138:141], v[204:207], v[28:31]
	v_mfma_f32_16x16x32_bf16 v[20:23], v[164:167], v[204:207], v[20:23]
	v_mfma_f32_16x16x32_bf16 v[12:15], v[138:141], v[234:237], v[12:15]
	v_mfma_f32_16x16x32_bf16 v[4:7], v[164:167], v[234:237], v[4:7]
	v_mfma_f32_16x16x32_bf16 v[60:63], v[160:163], v[192:195], v[60:63]
	v_mfma_f32_16x16x32_bf16 v[52:55], v[168:171], v[192:195], v[52:55]
	v_mfma_f32_16x16x32_bf16 v[44:47], v[160:163], v[200:203], v[44:47]
	v_mfma_f32_16x16x32_bf16 v[36:39], v[168:171], v[200:203], v[36:39]
	v_mfma_f32_16x16x32_bf16 v[28:31], v[160:163], v[208:211], v[28:31]
	v_mfma_f32_16x16x32_bf16 v[20:23], v[168:171], v[208:211], v[20:23]
	v_mfma_f32_16x16x32_bf16 v[12:15], v[160:163], v[244:247], v[12:15]
	v_mfma_f32_16x16x32_bf16 v[4:7], v[168:171], v[244:247], v[4:7]
	s_setprio 0
	s_setprio 1
	v_mfma_f32_16x16x32_bf16 v[56:59], v[172:175], v[188:191], v[56:59]
	v_mfma_f32_16x16x32_bf16 v[48:51], v[180:183], v[188:191], v[48:51]
	v_mfma_f32_16x16x32_bf16 v[40:43], v[172:175], v[196:199], v[40:43]
	v_mfma_f32_16x16x32_bf16 v[32:35], v[180:183], v[196:199], v[32:35]
	v_mfma_f32_16x16x32_bf16 v[24:27], v[172:175], v[204:207], v[24:27]
	v_mfma_f32_16x16x32_bf16 v[16:19], v[180:183], v[204:207], v[16:19]
	v_mfma_f32_16x16x32_bf16 v[8:11], v[172:175], v[234:237], v[8:11]
	v_mfma_f32_16x16x32_bf16 v[0:3], v[180:183], v[234:237], v[0:3]
	v_mfma_f32_16x16x32_bf16 v[56:59], v[176:179], v[192:195], v[56:59]
	v_mfma_f32_16x16x32_bf16 v[48:51], v[184:187], v[192:195], v[48:51]
	v_mfma_f32_16x16x32_bf16 v[40:43], v[176:179], v[200:203], v[40:43]
	v_mfma_f32_16x16x32_bf16 v[32:35], v[184:187], v[200:203], v[32:35]
	v_mfma_f32_16x16x32_bf16 v[24:27], v[176:179], v[208:211], v[24:27]
	v_mfma_f32_16x16x32_bf16 v[16:19], v[184:187], v[208:211], v[16:19]
	v_mfma_f32_16x16x32_bf16 v[8:11], v[176:179], v[244:247], v[8:11]
	v_mfma_f32_16x16x32_bf16 v[0:3], v[184:187], v[244:247], v[0:3]
	s_setprio 0
	s_add_i32 s46, s46, 2
	s_add_u32 s44, s44, 0x100
	s_addc_u32 s45, s45, 0
	s_add_u32 s22, s22, 0x100
	s_addc_u32 s23, s23, 0
	s_add_u32 s24, s22, 0xfffc0080
	s_addc_u32 s25, s23, -1
	s_add_i32 s47, 0, 0x10000
	s_cmp_eq_u32 s46, 12
	s_cselect_b32 s27, s17, s25
	s_cselect_b32 s26, s42, s24
	v_add_u32_e32 v142, s47, v156
	s_cselect_b32 s25, s15, s45
	s_cselect_b32 s24, s43, s44
	s_add_i32 s50, 0, 0x14000
	s_barrier
	s_cmp_gt_u32 s46, 13
	s_cbranch_scc0 .LBB0_1295
	s_and_b64 vcc, exec, s[12:13]
	s_cbranch_vccz .LBB0_1298
	s_barrier
